# BRA/BRB GEMM epilogues: all 16 gate vectors fetched up front (dummy destination) so the epilogue's serial gate loads hit in cache
# baseline (speedup 1.0000x reference)
.LBB0_894:
	v_lshl_or_b32 v146, s53, 8, v153
	v_lshl_add_u32 v148, s22, 8, v1
	v_mov_b64_e32 v[150:151], s[8:9]
	v_ashrrev_i32_e32 v147, 31, v146
	v_mad_i64_i32 v[158:159], s[24:25], v148, s45, v[150:151]
	v_lshlrev_b64 v[146:147], 1, v[146:147]
	v_lshl_add_u64 v[162:163], v[158:159], 0, v[146:147]
	global_load_dwordx4 v[158:161], v[162:163], off
	s_mov_b32 s100, 0x60000
	s_mov_b32 s101, 0
	v_lshl_add_u64 v[238:239], v[162:163], 0, s[100:101]
	global_load_dwordx4 v[234:237], v[238:239], off
	global_load_dwordx4 v[234:237], v[238:239], off offset:256
	v_lshl_add_u64 v[238:239], v[238:239], 0, s[100:101]
	global_load_dwordx4 v[234:237], v[238:239], off
	global_load_dwordx4 v[234:237], v[238:239], off offset:256
	v_lshl_add_u64 v[238:239], v[238:239], 0, s[100:101]
	global_load_dwordx4 v[234:237], v[238:239], off
	global_load_dwordx4 v[234:237], v[238:239], off offset:256
	s_mov_b32 s100, 0x1e0000
	v_lshl_add_u64 v[238:239], v[238:239], 0, s[100:101]
	global_load_dwordx4 v[234:237], v[238:239], off
	global_load_dwordx4 v[234:237], v[238:239], off offset:256
	s_mov_b32 s100, 0x60000
	v_lshl_add_u64 v[238:239], v[238:239], 0, s[100:101]
	global_load_dwordx4 v[234:237], v[238:239], off
	global_load_dwordx4 v[234:237], v[238:239], off offset:256
	v_lshl_add_u64 v[238:239], v[238:239], 0, s[100:101]
	global_load_dwordx4 v[234:237], v[238:239], off
	global_load_dwordx4 v[234:237], v[238:239], off offset:256
	v_lshl_add_u64 v[238:239], v[238:239], 0, s[100:101]
	global_load_dwordx4 v[234:237], v[238:239], off
	global_load_dwordx4 v[234:237], v[238:239], off offset:256
	v_ashrrev_i32_e32 v149, 31, v148
	v_lshlrev_b64 v[164:165], 12, v[148:149]
	v_lshl_add_u64 v[164:165], s[6:7], 0, v[164:165]
	v_lshl_add_u64 v[170:171], v[164:165], 0, v[146:147]
	global_load_dwordx4 v[162:165], v[162:163], off offset:256
	v_or_b32_e32 v166, 16, v148
	v_mad_i64_i32 v[168:169], s[24:25], v166, s45, v[150:151]
	v_lshl_add_u64 v[168:169], v[168:169], 0, v[146:147]
	s_andn2_b64 vcc, exec, s[4:5]
	s_mov_b64 s[4:5], -1
	s_waitcnt vmcnt(0)
	v_lshlrev_b32_e32 v173, 16, v161
	v_and_b32_e32 v161, 0xffff0000, v161
	v_lshlrev_b32_e32 v149, 16, v158
	v_and_b32_e32 v158, 0xffff0000, v158
	v_lshlrev_b32_e32 v167, 16, v159
	v_and_b32_e32 v159, 0xffff0000, v159
	v_lshlrev_b32_e32 v172, 16, v160
	v_and_b32_e32 v160, 0xffff0000, v160
	v_mul_f32_e32 v161, 0xbfb8aa3b, v161
	v_mul_f32_e32 v149, 0xbfb8aa3b, v149
	v_mul_f32_e32 v158, 0xbfb8aa3b, v158
	v_mul_f32_e32 v167, 0xbfb8aa3b, v167
	v_mul_f32_e32 v159, 0xbfb8aa3b, v159
	v_mul_f32_e32 v172, 0xbfb8aa3b, v172
	v_mul_f32_e32 v160, 0xbfb8aa3b, v160
	v_mul_f32_e32 v173, 0xbfb8aa3b, v173
	v_exp_f32_e32 v161, v161
	v_exp_f32_e32 v149, v149
	v_exp_f32_e32 v158, v158
	v_exp_f32_e32 v167, v167
	v_exp_f32_e32 v159, v159
	v_exp_f32_e32 v172, v172
	v_exp_f32_e32 v160, v160
	v_exp_f32_e32 v173, v173
	v_add_f32_e32 v161, 1.0, v161
	v_add_f32_e32 v149, 1.0, v149
	v_add_f32_e32 v158, 1.0, v158
	v_add_f32_e32 v167, 1.0, v167
	v_add_f32_e32 v159, 1.0, v159
	v_add_f32_e32 v172, 1.0, v172
	v_add_f32_e32 v160, 1.0, v160
	v_add_f32_e32 v173, 1.0, v173
	v_rcp_f32_e32 v161, v161
	v_rcp_f32_e32 v149, v149
	v_rcp_f32_e32 v158, v158
	v_rcp_f32_e32 v167, v167
	v_rcp_f32_e32 v159, v159
	v_rcp_f32_e32 v172, v172
	v_rcp_f32_e32 v160, v160
	v_rcp_f32_e32 v173, v173
	v_mul_f32_e32 v125, v125, v161
	v_mul_f32_e32 v126, v126, v149
	v_mul_f32_e32 v127, v127, v158
	v_mul_f32_e32 v128, v128, v167
	v_mul_f32_e32 v129, v129, v159
	v_mul_f32_e32 v149, v122, v172
	v_mul_f32_e32 v158, v123, v160
	v_mul_f32_e32 v159, v124, v173
	v_cvt_pk_bf16_f32 v122, v126, v127
	v_cvt_pk_bf16_f32 v123, v128, v129
	v_cvt_pk_bf16_f32 v124, v149, v158
	v_cvt_pk_bf16_f32 v125, v159, v125
	global_store_dwordx4 v[170:171], v[122:125], off
	global_load_dwordx4 v[124:127], v[168:169], off
	v_and_b32_e32 v149, 0xffff0000, v162
	v_lshlrev_b32_e32 v123, 16, v162
	v_lshlrev_b32_e32 v160, 16, v163
	v_and_b32_e32 v161, 0xffff0000, v163
	v_lshlrev_b32_e32 v162, 16, v164
	v_and_b32_e32 v163, 0xffff0000, v164
	v_lshlrev_b32_e32 v164, 16, v165
	v_and_b32_e32 v165, 0xffff0000, v165
	v_mul_f32_e32 v165, 0xbfb8aa3b, v165
	v_mul_f32_e32 v123, 0xbfb8aa3b, v123
	v_mul_f32_e32 v149, 0xbfb8aa3b, v149
	v_mul_f32_e32 v160, 0xbfb8aa3b, v160
	v_mul_f32_e32 v161, 0xbfb8aa3b, v161
	v_mul_f32_e32 v162, 0xbfb8aa3b, v162
	v_mul_f32_e32 v163, 0xbfb8aa3b, v163
	v_mul_f32_e32 v164, 0xbfb8aa3b, v164
	v_exp_f32_e32 v165, v165
	v_exp_f32_e32 v123, v123
	v_exp_f32_e32 v149, v149
	v_exp_f32_e32 v160, v160
	v_exp_f32_e32 v161, v161
	v_exp_f32_e32 v162, v162
	v_exp_f32_e32 v163, v163
	v_exp_f32_e32 v164, v164
	v_add_f32_e32 v165, 1.0, v165
	v_add_f32_e32 v123, 1.0, v123
	v_add_f32_e32 v149, 1.0, v149
	v_add_f32_e32 v160, 1.0, v160
	v_add_f32_e32 v161, 1.0, v161
	v_add_f32_e32 v162, 1.0, v162
	v_add_f32_e32 v163, 1.0, v163
	v_add_f32_e32 v164, 1.0, v164
	v_rcp_f32_e32 v165, v165
	v_rcp_f32_e32 v123, v123
	v_rcp_f32_e32 v149, v149
	v_rcp_f32_e32 v160, v160
	v_rcp_f32_e32 v161, v161
	v_rcp_f32_e32 v162, v162
	v_rcp_f32_e32 v163, v163
	v_rcp_f32_e32 v164, v164
	v_mul_f32_e32 v117, v117, v165
	v_mul_f32_e32 v118, v118, v123
	v_mul_f32_e32 v119, v119, v149
	v_mul_f32_e32 v120, v120, v160
	v_mul_f32_e32 v121, v121, v161
	v_mul_f32_e32 v123, v114, v162
	v_mul_f32_e32 v149, v115, v163
	v_mul_f32_e32 v160, v116, v164
	v_cvt_pk_bf16_f32 v114, v118, v119
	v_cvt_pk_bf16_f32 v115, v120, v121
	v_cvt_pk_bf16_f32 v116, v123, v149
	v_cvt_pk_bf16_f32 v117, v160, v117
	global_store_dwordx4 v[170:171], v[114:117], off offset:256
	global_load_dwordx4 v[114:117], v[168:169], off offset:256
	v_ashrrev_i32_e32 v167, 31, v166
	v_lshlrev_b64 v[158:159], 12, v[166:167]
	v_or_b32_e32 v122, 32, v148
	v_lshl_add_u64 v[158:159], s[6:7], 0, v[158:159]
	v_mad_i64_i32 v[128:129], s[24:25], v122, s45, v[150:151]
	v_lshl_add_u64 v[158:159], v[158:159], 0, v[146:147]
	v_lshl_add_u64 v[128:129], v[128:129], 0, v[146:147]
	s_waitcnt vmcnt(2)
	v_lshlrev_b32_e32 v118, 16, v124
	v_and_b32_e32 v119, 0xffff0000, v124
	v_lshlrev_b32_e32 v123, 16, v126
	v_and_b32_e32 v124, 0xffff0000, v126
	v_and_b32_e32 v126, 0xffff0000, v127
	v_lshlrev_b32_e32 v120, 16, v125
	v_and_b32_e32 v121, 0xffff0000, v125
	v_lshlrev_b32_e32 v125, 16, v127
	v_mul_f32_e32 v126, 0xbfb8aa3b, v126
	v_mul_f32_e32 v118, 0xbfb8aa3b, v118
	v_mul_f32_e32 v119, 0xbfb8aa3b, v119
	v_mul_f32_e32 v120, 0xbfb8aa3b, v120
	v_mul_f32_e32 v121, 0xbfb8aa3b, v121
	v_mul_f32_e32 v123, 0xbfb8aa3b, v123
	v_mul_f32_e32 v124, 0xbfb8aa3b, v124
	v_mul_f32_e32 v125, 0xbfb8aa3b, v125
	v_exp_f32_e32 v126, v126
	v_exp_f32_e32 v118, v118
	v_exp_f32_e32 v119, v119
	v_exp_f32_e32 v120, v120
	v_exp_f32_e32 v121, v121
	v_exp_f32_e32 v123, v123
	v_exp_f32_e32 v124, v124
	v_exp_f32_e32 v125, v125
	v_add_f32_e32 v126, 1.0, v126
	v_add_f32_e32 v118, 1.0, v118
	v_add_f32_e32 v119, 1.0, v119
	v_add_f32_e32 v120, 1.0, v120
	v_add_f32_e32 v121, 1.0, v121
	v_add_f32_e32 v123, 1.0, v123
	v_add_f32_e32 v124, 1.0, v124
	v_add_f32_e32 v125, 1.0, v125
	v_rcp_f32_e32 v126, v126
	v_rcp_f32_e32 v118, v118
	v_rcp_f32_e32 v119, v119
	v_rcp_f32_e32 v120, v120
	v_rcp_f32_e32 v121, v121
	v_rcp_f32_e32 v123, v123
	v_rcp_f32_e32 v124, v124
	v_rcp_f32_e32 v125, v125
	v_mul_f32_e32 v109, v109, v126
	v_mul_f32_e32 v110, v110, v118
	v_mul_f32_e32 v111, v111, v119
	v_mul_f32_e32 v112, v112, v120
	v_mul_f32_e32 v113, v113, v121
	v_mul_f32_e32 v118, v106, v123
	v_mul_f32_e32 v119, v107, v124
	v_mul_f32_e32 v120, v108, v125
	v_cvt_pk_bf16_f32 v106, v110, v111
	v_cvt_pk_bf16_f32 v107, v112, v113
	v_cvt_pk_bf16_f32 v108, v118, v119
	v_cvt_pk_bf16_f32 v109, v120, v109
	global_store_dwordx4 v[158:159], v[106:109], off
	global_load_dwordx4 v[106:109], v[128:129], off
	s_waitcnt vmcnt(2)
	v_lshlrev_b32_e32 v110, 16, v114
	v_and_b32_e32 v111, 0xffff0000, v114
	v_lshlrev_b32_e32 v112, 16, v115
	v_and_b32_e32 v113, 0xffff0000, v115
	v_lshlrev_b32_e32 v114, 16, v116
	v_and_b32_e32 v115, 0xffff0000, v116
	v_lshlrev_b32_e32 v116, 16, v117
	v_and_b32_e32 v117, 0xffff0000, v117
	v_mul_f32_e32 v117, 0xbfb8aa3b, v117
	v_mul_f32_e32 v110, 0xbfb8aa3b, v110
	v_mul_f32_e32 v111, 0xbfb8aa3b, v111
	v_mul_f32_e32 v112, 0xbfb8aa3b, v112
	v_mul_f32_e32 v113, 0xbfb8aa3b, v113
	v_mul_f32_e32 v114, 0xbfb8aa3b, v114
	v_mul_f32_e32 v115, 0xbfb8aa3b, v115
	v_mul_f32_e32 v116, 0xbfb8aa3b, v116
	v_exp_f32_e32 v117, v117
	v_exp_f32_e32 v110, v110
	v_exp_f32_e32 v111, v111
	v_exp_f32_e32 v112, v112
	v_exp_f32_e32 v113, v113
	v_exp_f32_e32 v114, v114
	v_exp_f32_e32 v115, v115
	v_exp_f32_e32 v116, v116
	v_add_f32_e32 v117, 1.0, v117
	v_add_f32_e32 v110, 1.0, v110
	v_add_f32_e32 v111, 1.0, v111
	v_add_f32_e32 v112, 1.0, v112
	v_add_f32_e32 v113, 1.0, v113
	v_add_f32_e32 v114, 1.0, v114
	v_add_f32_e32 v115, 1.0, v115
	v_add_f32_e32 v116, 1.0, v116
	v_rcp_f32_e32 v117, v117
	v_rcp_f32_e32 v110, v110
	v_rcp_f32_e32 v111, v111
	v_rcp_f32_e32 v112, v112
	v_rcp_f32_e32 v113, v113
	v_rcp_f32_e32 v114, v114
	v_rcp_f32_e32 v115, v115
	v_rcp_f32_e32 v116, v116
	v_mul_f32_e32 v101, v101, v117
	v_mul_f32_e32 v102, v102, v110
	v_mul_f32_e32 v103, v103, v111
	v_mul_f32_e32 v104, v104, v112
	v_mul_f32_e32 v105, v105, v113
	v_mul_f32_e32 v110, v98, v114
	v_mul_f32_e32 v111, v99, v115
	v_mul_f32_e32 v112, v100, v116
	v_cvt_pk_bf16_f32 v98, v102, v103
	v_cvt_pk_bf16_f32 v99, v104, v105
	v_cvt_pk_bf16_f32 v100, v110, v111
	v_cvt_pk_bf16_f32 v101, v112, v101
	global_store_dwordx4 v[158:159], v[98:101], off offset:256
	global_load_dwordx4 v[98:101], v[128:129], off offset:256
	v_ashrrev_i32_e32 v123, 31, v122
	s_waitcnt vmcnt(2)
	v_and_b32_e32 v103, 0xffff0000, v106
	v_mul_f32_e32 v103, 0xbfb8aa3b, v103
	v_lshlrev_b32_e32 v102, 16, v106
	v_exp_f32_e32 v103, v103
	v_lshlrev_b32_e32 v104, 16, v107
	v_lshlrev_b32_e32 v106, 16, v108
	v_mul_f32_e32 v102, 0xbfb8aa3b, v102
	v_mul_f32_e32 v104, 0xbfb8aa3b, v104
	v_mul_f32_e32 v106, 0xbfb8aa3b, v106
	v_exp_f32_e32 v102, v102
	v_and_b32_e32 v105, 0xffff0000, v107
	v_and_b32_e32 v107, 0xffff0000, v108
	v_lshlrev_b32_e32 v108, 16, v109
	v_and_b32_e32 v109, 0xffff0000, v109
	v_exp_f32_e32 v104, v104
	v_exp_f32_e32 v106, v106
	v_mul_f32_e32 v105, 0xbfb8aa3b, v105
	v_mul_f32_e32 v107, 0xbfb8aa3b, v107
	v_mul_f32_e32 v109, 0xbfb8aa3b, v109
	v_add_f32_e32 v103, 1.0, v103
	v_mul_f32_e32 v108, 0xbfb8aa3b, v108
	v_exp_f32_e32 v105, v105
	v_exp_f32_e32 v107, v107
	v_exp_f32_e32 v109, v109
	v_rcp_f32_e32 v103, v103
	v_exp_f32_e32 v108, v108
	v_add_f32_e32 v102, 1.0, v102
	v_add_f32_e32 v104, 1.0, v104
	v_add_f32_e32 v106, 1.0, v106
	v_rcp_f32_e32 v102, v102
	v_rcp_f32_e32 v104, v104
	v_rcp_f32_e32 v106, v106
	v_add_f32_e32 v105, 1.0, v105
	v_add_f32_e32 v107, 1.0, v107
	v_mul_f32_e32 v95, v95, v103
	v_add_f32_e32 v103, 1.0, v109
	v_add_f32_e32 v108, 1.0, v108
	v_rcp_f32_e32 v105, v105
	v_rcp_f32_e32 v107, v107
	v_rcp_f32_e32 v103, v103
	v_mul_f32_e32 v94, v94, v102
	v_rcp_f32_e32 v102, v108
	v_mul_f32_e32 v96, v96, v104
	v_mul_f32_e32 v104, v90, v106
	v_cvt_pk_bf16_f32 v90, v94, v95
	v_lshlrev_b64 v[94:95], 12, v[122:123]
	v_lshl_add_u64 v[94:95], s[6:7], 0, v[94:95]
	v_mul_f32_e32 v97, v97, v105
	v_mul_f32_e32 v105, v91, v107
	v_mul_f32_e32 v93, v93, v103
	v_cvt_pk_bf16_f32 v91, v96, v97
	v_lshl_add_u64 v[94:95], v[94:95], 0, v[146:147]
	v_or_b32_e32 v96, 48, v148
	v_mul_f32_e32 v102, v92, v102
	v_cvt_pk_bf16_f32 v92, v104, v105
	v_cvt_pk_bf16_f32 v93, v102, v93
	global_store_dwordx4 v[94:95], v[90:93], off
	s_waitcnt vmcnt(1)
	v_lshlrev_b32_e32 v106, 16, v101
	v_and_b32_e32 v101, 0xffff0000, v101
	v_mad_i64_i32 v[90:91], s[24:25], v96, s45, v[150:151]
	v_lshl_add_u64 v[102:103], v[90:91], 0, v[146:147]
	global_load_dwordx4 v[90:93], v[102:103], off
	v_lshlrev_b32_e32 v97, 16, v98
	v_and_b32_e32 v98, 0xffff0000, v98
	v_lshlrev_b32_e32 v104, 16, v99
	v_and_b32_e32 v99, 0xffff0000, v99
	v_lshlrev_b32_e32 v105, 16, v100
	v_and_b32_e32 v100, 0xffff0000, v100
	v_mul_f32_e32 v101, 0xbfb8aa3b, v101
	v_mul_f32_e32 v97, 0xbfb8aa3b, v97
	v_mul_f32_e32 v98, 0xbfb8aa3b, v98
	v_mul_f32_e32 v104, 0xbfb8aa3b, v104
	v_mul_f32_e32 v99, 0xbfb8aa3b, v99
	v_mul_f32_e32 v105, 0xbfb8aa3b, v105
	v_mul_f32_e32 v100, 0xbfb8aa3b, v100
	v_mul_f32_e32 v106, 0xbfb8aa3b, v106
	v_exp_f32_e32 v101, v101
	v_exp_f32_e32 v97, v97
	v_exp_f32_e32 v98, v98
	v_exp_f32_e32 v104, v104
	v_exp_f32_e32 v99, v99
	v_exp_f32_e32 v105, v105
	v_exp_f32_e32 v100, v100
	v_exp_f32_e32 v106, v106
	v_add_f32_e32 v101, 1.0, v101
	v_add_f32_e32 v97, 1.0, v97
	v_add_f32_e32 v98, 1.0, v98
	v_add_f32_e32 v104, 1.0, v104
	v_add_f32_e32 v99, 1.0, v99
	v_add_f32_e32 v105, 1.0, v105
	v_add_f32_e32 v100, 1.0, v100
	v_add_f32_e32 v106, 1.0, v106
	v_rcp_f32_e32 v101, v101
	v_rcp_f32_e32 v97, v97
	v_rcp_f32_e32 v98, v98
	v_rcp_f32_e32 v104, v104
	v_rcp_f32_e32 v99, v99
	v_rcp_f32_e32 v105, v105
	v_rcp_f32_e32 v100, v100
	v_rcp_f32_e32 v106, v106
	v_mul_f32_e32 v85, v85, v101
	v_mul_f32_e32 v86, v86, v97
	v_mul_f32_e32 v87, v87, v98
	v_mul_f32_e32 v88, v88, v104
	v_mul_f32_e32 v89, v89, v99
	v_mul_f32_e32 v97, v82, v105
	v_mul_f32_e32 v98, v83, v100
	v_mul_f32_e32 v99, v84, v106
	v_cvt_pk_bf16_f32 v82, v86, v87
	v_cvt_pk_bf16_f32 v83, v88, v89
	v_cvt_pk_bf16_f32 v84, v97, v98
	v_cvt_pk_bf16_f32 v85, v99, v85
	global_store_dwordx4 v[94:95], v[82:85], off offset:256
	global_load_dwordx4 v[82:85], v[102:103], off offset:256
	v_ashrrev_i32_e32 v97, 31, v96
	s_waitcnt vmcnt(2)
	v_and_b32_e32 v87, 0xffff0000, v90
	v_lshlrev_b32_e32 v88, 16, v91
	v_lshlrev_b32_e32 v86, 16, v90
	v_mul_f32_e32 v87, 0xbfb8aa3b, v87
	v_mul_f32_e32 v88, 0xbfb8aa3b, v88
	v_mul_f32_e32 v86, 0xbfb8aa3b, v86
	v_exp_f32_e32 v87, v87
	v_exp_f32_e32 v88, v88
	v_exp_f32_e32 v86, v86
	v_and_b32_e32 v89, 0xffff0000, v91
	v_add_f32_e32 v87, 1.0, v87
	v_add_f32_e32 v88, 1.0, v88
	v_mul_f32_e32 v89, 0xbfb8aa3b, v89
	v_add_f32_e32 v86, 1.0, v86
	v_rcp_f32_e32 v87, v87
	v_rcp_f32_e32 v88, v88
	v_rcp_f32_e32 v86, v86
	v_exp_f32_e32 v89, v89
	v_mul_f32_e32 v79, v79, v87
	v_mul_f32_e32 v80, v80, v88
	v_lshlrev_b32_e32 v87, 16, v92
	v_and_b32_e32 v88, 0xffff0000, v92
	v_mul_f32_e32 v78, v78, v86
	v_add_f32_e32 v86, 1.0, v89
	v_mul_f32_e32 v87, 0xbfb8aa3b, v87
	v_mul_f32_e32 v88, 0xbfb8aa3b, v88
	v_rcp_f32_e32 v86, v86
	v_exp_f32_e32 v87, v87
	v_exp_f32_e32 v88, v88
	v_and_b32_e32 v89, 0xffff0000, v93
	v_mul_f32_e32 v81, v81, v86
	v_add_f32_e32 v86, 1.0, v87
	v_add_f32_e32 v87, 1.0, v88
	v_lshlrev_b32_e32 v88, 16, v93
	v_mul_f32_e32 v89, 0xbfb8aa3b, v89
	v_mul_f32_e32 v88, 0xbfb8aa3b, v88
	v_exp_f32_e32 v89, v89
	v_exp_f32_e32 v88, v88
	v_rcp_f32_e32 v86, v86
	v_rcp_f32_e32 v87, v87
	v_add_f32_e32 v89, 1.0, v89
	v_add_f32_e32 v88, 1.0, v88
	v_rcp_f32_e32 v89, v89
	v_rcp_f32_e32 v88, v88
	v_mul_f32_e32 v86, v74, v86
	v_cvt_pk_bf16_f32 v74, v78, v79
	v_lshlrev_b64 v[78:79], 12, v[96:97]
	v_lshl_add_u64 v[78:79], s[6:7], 0, v[78:79]
	v_mul_f32_e32 v87, v75, v87
	v_mul_f32_e32 v77, v77, v89
	v_cvt_pk_bf16_f32 v75, v80, v81
	v_lshl_add_u64 v[78:79], v[78:79], 0, v[146:147]
	v_add_u32_e32 v80, 0x80, v148
	v_mul_f32_e32 v88, v76, v88
	v_cvt_pk_bf16_f32 v76, v86, v87
	v_cvt_pk_bf16_f32 v77, v88, v77
	global_store_dwordx4 v[78:79], v[74:77], off
	s_waitcnt vmcnt(1)
	v_lshlrev_b32_e32 v81, 16, v82
	v_and_b32_e32 v82, 0xffff0000, v82
	v_mad_i64_i32 v[74:75], s[24:25], v80, s45, v[150:151]
	v_lshl_add_u64 v[86:87], v[74:75], 0, v[146:147]
	global_load_dwordx4 v[74:77], v[86:87], off
	v_mul_f32_e32 v81, 0xbfb8aa3b, v81
	v_mul_f32_e32 v82, 0xbfb8aa3b, v82
	v_exp_f32_e32 v81, v81
	v_exp_f32_e32 v82, v82
	v_lshlrev_b32_e32 v88, 16, v83
	v_and_b32_e32 v83, 0xffff0000, v83
	v_add_f32_e32 v81, 1.0, v81
	v_add_f32_e32 v82, 1.0, v82
	v_mul_f32_e32 v83, 0xbfb8aa3b, v83
	v_rcp_f32_e32 v81, v81
	v_rcp_f32_e32 v82, v82
	v_exp_f32_e32 v83, v83
	v_mul_f32_e32 v88, 0xbfb8aa3b, v88
	v_mul_f32_e32 v70, v70, v81
	v_mul_f32_e32 v71, v71, v82
	v_add_f32_e32 v81, 1.0, v83
	v_lshlrev_b32_e32 v82, 16, v84
	v_and_b32_e32 v83, 0xffff0000, v84
	v_mul_f32_e32 v82, 0xbfb8aa3b, v82
	v_mul_f32_e32 v83, 0xbfb8aa3b, v83
	v_rcp_f32_e32 v81, v81
	v_exp_f32_e32 v82, v82
	v_exp_f32_e32 v83, v83
	v_and_b32_e32 v84, 0xffff0000, v85
	v_mul_f32_e32 v73, v73, v81
	v_add_f32_e32 v81, 1.0, v82
	v_add_f32_e32 v82, 1.0, v83
	v_lshlrev_b32_e32 v83, 16, v85
	v_mul_f32_e32 v84, 0xbfb8aa3b, v84
	v_mul_f32_e32 v83, 0xbfb8aa3b, v83
	v_exp_f32_e32 v84, v84
	v_exp_f32_e32 v88, v88
	v_exp_f32_e32 v83, v83
	v_rcp_f32_e32 v81, v81
	v_add_f32_e32 v84, 1.0, v84
	v_add_f32_e32 v88, 1.0, v88
	v_add_f32_e32 v83, 1.0, v83
	v_rcp_f32_e32 v84, v84
	v_rcp_f32_e32 v88, v88
	v_rcp_f32_e32 v82, v82
	v_rcp_f32_e32 v83, v83
	v_mul_f32_e32 v69, v69, v84
	v_mul_f32_e32 v72, v72, v88
	v_mul_f32_e32 v81, v66, v81
	v_mul_f32_e32 v82, v67, v82
	v_mul_f32_e32 v83, v68, v83
	v_cvt_pk_bf16_f32 v66, v70, v71
	v_cvt_pk_bf16_f32 v67, v72, v73
	v_cvt_pk_bf16_f32 v68, v81, v82
	v_cvt_pk_bf16_f32 v69, v83, v69
	global_store_dwordx4 v[78:79], v[66:69], off offset:256
	global_load_dwordx4 v[66:69], v[86:87], off offset:256
	v_ashrrev_i32_e32 v81, 31, v80
	s_waitcnt vmcnt(2)
	v_and_b32_e32 v71, 0xffff0000, v74
	v_lshlrev_b32_e32 v72, 16, v75
	v_lshlrev_b32_e32 v70, 16, v74
	v_mul_f32_e32 v71, 0xbfb8aa3b, v71
	v_mul_f32_e32 v72, 0xbfb8aa3b, v72
	v_mul_f32_e32 v70, 0xbfb8aa3b, v70
	v_exp_f32_e32 v71, v71
	v_exp_f32_e32 v72, v72
	v_exp_f32_e32 v70, v70
	v_and_b32_e32 v73, 0xffff0000, v75
	v_add_f32_e32 v71, 1.0, v71
	v_add_f32_e32 v72, 1.0, v72
	v_add_f32_e32 v70, 1.0, v70
	v_rcp_f32_e32 v71, v71
	v_rcp_f32_e32 v72, v72
	v_mul_f32_e32 v73, 0xbfb8aa3b, v73
	v_rcp_f32_e32 v70, v70
	v_exp_f32_e32 v73, v73
	v_mul_f32_e32 v63, v63, v71
	v_mul_f32_e32 v64, v64, v72
	v_lshlrev_b32_e32 v71, 16, v76
	v_and_b32_e32 v72, 0xffff0000, v76
	v_mul_f32_e32 v62, v62, v70
	v_add_f32_e32 v70, 1.0, v73
	v_mul_f32_e32 v71, 0xbfb8aa3b, v71
	v_mul_f32_e32 v72, 0xbfb8aa3b, v72
	v_rcp_f32_e32 v70, v70
	v_exp_f32_e32 v71, v71
	v_exp_f32_e32 v72, v72
	v_and_b32_e32 v73, 0xffff0000, v77
	v_mul_f32_e32 v65, v65, v70
	v_add_f32_e32 v70, 1.0, v71
	v_add_f32_e32 v71, 1.0, v72
	v_lshlrev_b32_e32 v72, 16, v77
	v_mul_f32_e32 v73, 0xbfb8aa3b, v73
	v_mul_f32_e32 v72, 0xbfb8aa3b, v72
	v_exp_f32_e32 v73, v73
	v_exp_f32_e32 v72, v72
	v_rcp_f32_e32 v70, v70
	v_rcp_f32_e32 v71, v71
	v_add_f32_e32 v73, 1.0, v73
	v_add_f32_e32 v72, 1.0, v72
	v_rcp_f32_e32 v73, v73
	v_rcp_f32_e32 v72, v72
	v_mul_f32_e32 v70, v58, v70
	v_cvt_pk_bf16_f32 v58, v62, v63
	v_lshlrev_b64 v[62:63], 12, v[80:81]
	v_lshl_add_u64 v[62:63], s[6:7], 0, v[62:63]
	v_mul_f32_e32 v71, v59, v71
	v_mul_f32_e32 v61, v61, v73
	v_cvt_pk_bf16_f32 v59, v64, v65
	v_lshl_add_u64 v[62:63], v[62:63], 0, v[146:147]
	v_add_u32_e32 v64, 0x90, v148
	v_mul_f32_e32 v72, v60, v72
	v_cvt_pk_bf16_f32 v60, v70, v71
	v_cvt_pk_bf16_f32 v61, v72, v61
	global_store_dwordx4 v[62:63], v[58:61], off
	s_waitcnt vmcnt(1)
	v_lshlrev_b32_e32 v65, 16, v66
	v_and_b32_e32 v66, 0xffff0000, v66
	v_mad_i64_i32 v[58:59], s[24:25], v64, s45, v[150:151]
	v_lshl_add_u64 v[70:71], v[58:59], 0, v[146:147]
	global_load_dwordx4 v[58:61], v[70:71], off
	v_mul_f32_e32 v65, 0xbfb8aa3b, v65
	v_mul_f32_e32 v66, 0xbfb8aa3b, v66
	v_exp_f32_e32 v65, v65
	v_exp_f32_e32 v66, v66
	v_lshlrev_b32_e32 v72, 16, v67
	v_and_b32_e32 v67, 0xffff0000, v67
	v_add_f32_e32 v65, 1.0, v65
	v_add_f32_e32 v66, 1.0, v66
	v_mul_f32_e32 v67, 0xbfb8aa3b, v67
	v_rcp_f32_e32 v65, v65
	v_rcp_f32_e32 v66, v66
	v_exp_f32_e32 v67, v67
	v_mul_f32_e32 v72, 0xbfb8aa3b, v72
	v_mul_f32_e32 v54, v54, v65
	v_mul_f32_e32 v55, v55, v66
	v_add_f32_e32 v65, 1.0, v67
	v_lshlrev_b32_e32 v66, 16, v68
	v_and_b32_e32 v67, 0xffff0000, v68
	v_mul_f32_e32 v66, 0xbfb8aa3b, v66
	v_mul_f32_e32 v67, 0xbfb8aa3b, v67
	v_rcp_f32_e32 v65, v65
	v_exp_f32_e32 v66, v66
	v_exp_f32_e32 v67, v67
	v_and_b32_e32 v68, 0xffff0000, v69
	v_mul_f32_e32 v57, v57, v65
	v_add_f32_e32 v65, 1.0, v66
	v_add_f32_e32 v66, 1.0, v67
	v_lshlrev_b32_e32 v67, 16, v69
	v_mul_f32_e32 v68, 0xbfb8aa3b, v68
	v_mul_f32_e32 v67, 0xbfb8aa3b, v67
	v_exp_f32_e32 v68, v68
	v_exp_f32_e32 v72, v72
	v_exp_f32_e32 v67, v67
	v_rcp_f32_e32 v65, v65
	v_add_f32_e32 v68, 1.0, v68
	v_add_f32_e32 v72, 1.0, v72
	v_add_f32_e32 v67, 1.0, v67
	v_rcp_f32_e32 v68, v68
	v_rcp_f32_e32 v72, v72
	v_rcp_f32_e32 v66, v66
	v_rcp_f32_e32 v67, v67
	v_mul_f32_e32 v53, v53, v68
	v_mul_f32_e32 v56, v56, v72
	v_mul_f32_e32 v65, v50, v65
	v_mul_f32_e32 v66, v51, v66
	v_mul_f32_e32 v67, v52, v67
	v_cvt_pk_bf16_f32 v50, v54, v55
	v_cvt_pk_bf16_f32 v51, v56, v57
	v_cvt_pk_bf16_f32 v52, v65, v66
	v_cvt_pk_bf16_f32 v53, v67, v53
	global_store_dwordx4 v[62:63], v[50:53], off offset:256
	global_load_dwordx4 v[50:53], v[70:71], off offset:256
	v_ashrrev_i32_e32 v65, 31, v64
	s_waitcnt vmcnt(2)
	v_and_b32_e32 v55, 0xffff0000, v58
	v_lshlrev_b32_e32 v56, 16, v59
	v_lshlrev_b32_e32 v54, 16, v58
	v_mul_f32_e32 v55, 0xbfb8aa3b, v55
	v_mul_f32_e32 v56, 0xbfb8aa3b, v56
	v_mul_f32_e32 v54, 0xbfb8aa3b, v54
	v_exp_f32_e32 v55, v55
	v_exp_f32_e32 v56, v56
	v_exp_f32_e32 v54, v54
	v_and_b32_e32 v57, 0xffff0000, v59
	v_add_f32_e32 v55, 1.0, v55
	v_add_f32_e32 v56, 1.0, v56
	v_add_f32_e32 v54, 1.0, v54
	v_rcp_f32_e32 v55, v55
	v_rcp_f32_e32 v56, v56
	v_mul_f32_e32 v57, 0xbfb8aa3b, v57
	v_rcp_f32_e32 v54, v54
	v_exp_f32_e32 v57, v57
	v_mul_f32_e32 v47, v47, v55
	v_mul_f32_e32 v48, v48, v56
	v_lshlrev_b32_e32 v55, 16, v60
	v_and_b32_e32 v56, 0xffff0000, v60
	v_mul_f32_e32 v46, v46, v54
	v_add_f32_e32 v54, 1.0, v57
	v_mul_f32_e32 v55, 0xbfb8aa3b, v55
	v_mul_f32_e32 v56, 0xbfb8aa3b, v56
	v_rcp_f32_e32 v54, v54
	v_exp_f32_e32 v55, v55
	v_exp_f32_e32 v56, v56
	v_and_b32_e32 v57, 0xffff0000, v61
	v_mul_f32_e32 v49, v49, v54
	v_add_f32_e32 v54, 1.0, v55
	v_add_f32_e32 v55, 1.0, v56
	v_lshlrev_b32_e32 v56, 16, v61
	v_mul_f32_e32 v57, 0xbfb8aa3b, v57
	v_mul_f32_e32 v56, 0xbfb8aa3b, v56
	v_exp_f32_e32 v57, v57
	v_exp_f32_e32 v56, v56
	v_rcp_f32_e32 v54, v54
	v_rcp_f32_e32 v55, v55
	v_add_f32_e32 v57, 1.0, v57
	v_add_f32_e32 v56, 1.0, v56
	v_rcp_f32_e32 v57, v57
	v_rcp_f32_e32 v56, v56
	v_mul_f32_e32 v54, v42, v54
	v_cvt_pk_bf16_f32 v42, v46, v47
	v_lshlrev_b64 v[46:47], 12, v[64:65]
	v_lshl_add_u64 v[46:47], s[6:7], 0, v[46:47]
	v_mul_f32_e32 v55, v43, v55
	v_mul_f32_e32 v45, v45, v57
	v_cvt_pk_bf16_f32 v43, v48, v49
	v_lshl_add_u64 v[46:47], v[46:47], 0, v[146:147]
	v_add_u32_e32 v48, 0xa0, v148
	v_mul_f32_e32 v56, v44, v56
	v_cvt_pk_bf16_f32 v44, v54, v55
	v_cvt_pk_bf16_f32 v45, v56, v45
	global_store_dwordx4 v[46:47], v[42:45], off
	s_waitcnt vmcnt(1)
	v_lshlrev_b32_e32 v49, 16, v50
	v_and_b32_e32 v50, 0xffff0000, v50
	v_mad_i64_i32 v[42:43], s[24:25], v48, s45, v[150:151]
	v_lshl_add_u64 v[54:55], v[42:43], 0, v[146:147]
	global_load_dwordx4 v[42:45], v[54:55], off
	v_mul_f32_e32 v49, 0xbfb8aa3b, v49
	v_mul_f32_e32 v50, 0xbfb8aa3b, v50
	v_exp_f32_e32 v49, v49
	v_exp_f32_e32 v50, v50
	v_lshlrev_b32_e32 v56, 16, v51
	v_and_b32_e32 v51, 0xffff0000, v51
	v_add_f32_e32 v49, 1.0, v49
	v_add_f32_e32 v50, 1.0, v50
	v_mul_f32_e32 v51, 0xbfb8aa3b, v51
	v_rcp_f32_e32 v49, v49
	v_rcp_f32_e32 v50, v50
	v_exp_f32_e32 v51, v51
	v_mul_f32_e32 v56, 0xbfb8aa3b, v56
	v_mul_f32_e32 v38, v38, v49
	v_mul_f32_e32 v39, v39, v50
	v_add_f32_e32 v49, 1.0, v51
	v_lshlrev_b32_e32 v50, 16, v52
	v_and_b32_e32 v51, 0xffff0000, v52
	v_mul_f32_e32 v50, 0xbfb8aa3b, v50
	v_mul_f32_e32 v51, 0xbfb8aa3b, v51
	v_rcp_f32_e32 v49, v49
	v_exp_f32_e32 v50, v50
	v_exp_f32_e32 v51, v51
	v_and_b32_e32 v52, 0xffff0000, v53
	v_mul_f32_e32 v41, v41, v49
	v_add_f32_e32 v49, 1.0, v50
	v_add_f32_e32 v50, 1.0, v51
	v_lshlrev_b32_e32 v51, 16, v53
	v_mul_f32_e32 v52, 0xbfb8aa3b, v52
	v_mul_f32_e32 v51, 0xbfb8aa3b, v51
	v_exp_f32_e32 v52, v52
	v_exp_f32_e32 v56, v56
	v_exp_f32_e32 v51, v51
	v_rcp_f32_e32 v49, v49
	v_add_f32_e32 v52, 1.0, v52
	v_add_f32_e32 v56, 1.0, v56
	v_add_f32_e32 v51, 1.0, v51
	v_rcp_f32_e32 v52, v52
	v_rcp_f32_e32 v56, v56
	v_rcp_f32_e32 v50, v50
	v_rcp_f32_e32 v51, v51
	v_mul_f32_e32 v37, v37, v52
	v_mul_f32_e32 v40, v40, v56
	v_mul_f32_e32 v49, v34, v49
	v_mul_f32_e32 v50, v35, v50
	v_mul_f32_e32 v51, v36, v51
	v_cvt_pk_bf16_f32 v34, v38, v39
	v_cvt_pk_bf16_f32 v35, v40, v41
	v_cvt_pk_bf16_f32 v36, v49, v50
	v_cvt_pk_bf16_f32 v37, v51, v37
	global_store_dwordx4 v[46:47], v[34:37], off offset:256
	global_load_dwordx4 v[34:37], v[54:55], off offset:256
	v_ashrrev_i32_e32 v49, 31, v48
	s_waitcnt vmcnt(2)
	v_and_b32_e32 v39, 0xffff0000, v42
	v_lshlrev_b32_e32 v40, 16, v43
	v_lshlrev_b32_e32 v38, 16, v42
	v_mul_f32_e32 v39, 0xbfb8aa3b, v39
	v_mul_f32_e32 v40, 0xbfb8aa3b, v40
	v_mul_f32_e32 v38, 0xbfb8aa3b, v38
	v_exp_f32_e32 v39, v39
	v_exp_f32_e32 v40, v40
	v_exp_f32_e32 v38, v38
	v_and_b32_e32 v41, 0xffff0000, v43
	v_add_f32_e32 v39, 1.0, v39
	v_add_f32_e32 v40, 1.0, v40
	v_add_f32_e32 v38, 1.0, v38
	v_rcp_f32_e32 v39, v39
	v_rcp_f32_e32 v40, v40
	v_mul_f32_e32 v41, 0xbfb8aa3b, v41
	v_rcp_f32_e32 v38, v38
	v_exp_f32_e32 v41, v41
	v_mul_f32_e32 v31, v31, v39
	v_mul_f32_e32 v32, v32, v40
	v_lshlrev_b32_e32 v39, 16, v44
	v_and_b32_e32 v40, 0xffff0000, v44
	v_mul_f32_e32 v30, v30, v38
	v_add_f32_e32 v38, 1.0, v41
	v_mul_f32_e32 v39, 0xbfb8aa3b, v39
	v_mul_f32_e32 v40, 0xbfb8aa3b, v40
	v_rcp_f32_e32 v38, v38
	v_exp_f32_e32 v39, v39
	v_exp_f32_e32 v40, v40
	v_and_b32_e32 v41, 0xffff0000, v45
	v_mul_f32_e32 v33, v33, v38
	v_add_f32_e32 v38, 1.0, v39
	v_add_f32_e32 v39, 1.0, v40
	v_lshlrev_b32_e32 v40, 16, v45
	v_mul_f32_e32 v41, 0xbfb8aa3b, v41
	v_mul_f32_e32 v40, 0xbfb8aa3b, v40
	v_exp_f32_e32 v41, v41
	v_exp_f32_e32 v40, v40
	v_rcp_f32_e32 v38, v38
	v_rcp_f32_e32 v39, v39
	v_add_f32_e32 v41, 1.0, v41
	v_add_f32_e32 v40, 1.0, v40
	v_rcp_f32_e32 v41, v41
	v_rcp_f32_e32 v40, v40
	v_mul_f32_e32 v38, v26, v38
	v_cvt_pk_bf16_f32 v26, v30, v31
	v_lshlrev_b64 v[30:31], 12, v[48:49]
	v_lshl_add_u64 v[30:31], s[6:7], 0, v[30:31]
	v_mul_f32_e32 v39, v27, v39
	v_mul_f32_e32 v29, v29, v41
	v_cvt_pk_bf16_f32 v27, v32, v33
	v_lshl_add_u64 v[30:31], v[30:31], 0, v[146:147]
	v_add_u32_e32 v32, 0xb0, v148
	v_mul_f32_e32 v40, v28, v40
	v_cvt_pk_bf16_f32 v28, v38, v39
	v_cvt_pk_bf16_f32 v29, v40, v29
	global_store_dwordx4 v[30:31], v[26:29], off
	s_waitcnt vmcnt(1)
	v_lshlrev_b32_e32 v33, 16, v34
	v_and_b32_e32 v34, 0xffff0000, v34
	v_mad_i64_i32 v[26:27], s[24:25], v32, s45, v[150:151]
	v_lshl_add_u64 v[38:39], v[26:27], 0, v[146:147]
	global_load_dwordx4 v[26:29], v[38:39], off
	v_mul_f32_e32 v33, 0xbfb8aa3b, v33
	v_mul_f32_e32 v34, 0xbfb8aa3b, v34
	v_exp_f32_e32 v33, v33
	v_exp_f32_e32 v34, v34
	v_lshlrev_b32_e32 v40, 16, v35
	v_and_b32_e32 v35, 0xffff0000, v35
	v_add_f32_e32 v33, 1.0, v33
	v_add_f32_e32 v34, 1.0, v34
	v_mul_f32_e32 v35, 0xbfb8aa3b, v35
	v_rcp_f32_e32 v33, v33
	v_rcp_f32_e32 v34, v34
	v_exp_f32_e32 v35, v35
	v_mul_f32_e32 v40, 0xbfb8aa3b, v40
	v_mul_f32_e32 v22, v22, v33
	v_mul_f32_e32 v23, v23, v34
	v_add_f32_e32 v33, 1.0, v35
	v_lshlrev_b32_e32 v34, 16, v36
	v_and_b32_e32 v35, 0xffff0000, v36
	v_mul_f32_e32 v34, 0xbfb8aa3b, v34
	v_mul_f32_e32 v35, 0xbfb8aa3b, v35
	v_rcp_f32_e32 v33, v33
	v_exp_f32_e32 v34, v34
	v_exp_f32_e32 v35, v35
	v_and_b32_e32 v36, 0xffff0000, v37
	v_mul_f32_e32 v25, v25, v33
	v_add_f32_e32 v33, 1.0, v34
	v_add_f32_e32 v34, 1.0, v35
	v_lshlrev_b32_e32 v35, 16, v37
	v_mul_f32_e32 v36, 0xbfb8aa3b, v36
	v_mul_f32_e32 v35, 0xbfb8aa3b, v35
	v_exp_f32_e32 v36, v36
	v_exp_f32_e32 v40, v40
	v_exp_f32_e32 v35, v35
	v_rcp_f32_e32 v33, v33
	v_add_f32_e32 v36, 1.0, v36
	v_add_f32_e32 v40, 1.0, v40
	v_add_f32_e32 v35, 1.0, v35
	v_rcp_f32_e32 v36, v36
	v_rcp_f32_e32 v40, v40
	v_rcp_f32_e32 v34, v34
	v_rcp_f32_e32 v35, v35
	v_mul_f32_e32 v21, v21, v36
	v_mul_f32_e32 v24, v24, v40
	v_mul_f32_e32 v33, v18, v33
	v_mul_f32_e32 v34, v19, v34
	v_mul_f32_e32 v35, v20, v35
	v_cvt_pk_bf16_f32 v18, v22, v23
	v_cvt_pk_bf16_f32 v19, v24, v25
	v_cvt_pk_bf16_f32 v20, v33, v34
	v_cvt_pk_bf16_f32 v21, v35, v21
	global_store_dwordx4 v[30:31], v[18:21], off offset:256
	global_load_dwordx4 v[18:21], v[38:39], off offset:256
	v_ashrrev_i32_e32 v33, 31, v32
	s_waitcnt vmcnt(2)
	v_and_b32_e32 v23, 0xffff0000, v26
	v_lshlrev_b32_e32 v24, 16, v27
	v_lshlrev_b32_e32 v22, 16, v26
	v_mul_f32_e32 v23, 0xbfb8aa3b, v23
	v_mul_f32_e32 v24, 0xbfb8aa3b, v24
	v_mul_f32_e32 v22, 0xbfb8aa3b, v22
	v_exp_f32_e32 v23, v23
	v_exp_f32_e32 v24, v24
	v_exp_f32_e32 v22, v22
	v_and_b32_e32 v25, 0xffff0000, v27
	v_add_f32_e32 v23, 1.0, v23
	v_add_f32_e32 v24, 1.0, v24
	v_add_f32_e32 v22, 1.0, v22
	v_rcp_f32_e32 v23, v23
	v_rcp_f32_e32 v24, v24
	v_mul_f32_e32 v25, 0xbfb8aa3b, v25
	v_rcp_f32_e32 v22, v22
	v_exp_f32_e32 v25, v25
	v_mul_f32_e32 v15, v15, v23
	v_mul_f32_e32 v16, v16, v24
	v_lshlrev_b32_e32 v23, 16, v28
	v_and_b32_e32 v24, 0xffff0000, v28
	v_mul_f32_e32 v14, v14, v22
	v_add_f32_e32 v22, 1.0, v25
	v_mul_f32_e32 v23, 0xbfb8aa3b, v23
	v_mul_f32_e32 v24, 0xbfb8aa3b, v24
	v_rcp_f32_e32 v22, v22
	v_exp_f32_e32 v23, v23
	v_exp_f32_e32 v24, v24
	v_and_b32_e32 v25, 0xffff0000, v29
	v_mul_f32_e32 v17, v17, v22
	v_add_f32_e32 v22, 1.0, v23
	v_add_f32_e32 v23, 1.0, v24
	v_lshlrev_b32_e32 v24, 16, v29
	v_mul_f32_e32 v24, 0xbfb8aa3b, v24
	v_mul_f32_e32 v25, 0xbfb8aa3b, v25
	v_exp_f32_e32 v24, v24
	v_exp_f32_e32 v25, v25
	v_rcp_f32_e32 v22, v22
	v_rcp_f32_e32 v23, v23
	v_add_f32_e32 v24, 1.0, v24
	v_add_f32_e32 v25, 1.0, v25
	v_rcp_f32_e32 v24, v24
	v_rcp_f32_e32 v25, v25
	v_mul_f32_e32 v22, v10, v22
	v_cvt_pk_bf16_f32 v10, v14, v15
	v_lshlrev_b64 v[14:15], 12, v[32:33]
	v_lshl_add_u64 v[14:15], s[6:7], 0, v[14:15]
	v_mul_f32_e32 v23, v11, v23
	v_mul_f32_e32 v24, v12, v24
	v_mul_f32_e32 v13, v13, v25
	v_cvt_pk_bf16_f32 v11, v16, v17
	v_cvt_pk_bf16_f32 v12, v22, v23
	v_lshl_add_u64 v[14:15], v[14:15], 0, v[146:147]
	v_cvt_pk_bf16_f32 v13, v24, v13
	global_store_dwordx4 v[14:15], v[10:13], off
	s_waitcnt vmcnt(1)
	v_lshlrev_b32_e32 v16, 16, v18
	v_mul_f32_e32 v16, 0xbfb8aa3b, v16
	v_and_b32_e32 v11, 0xffff0000, v18
	v_lshlrev_b32_e32 v12, 16, v19
	v_mul_f32_e32 v11, 0xbfb8aa3b, v11
	v_mul_f32_e32 v12, 0xbfb8aa3b, v12
	v_exp_f32_e32 v11, v11
	v_exp_f32_e32 v12, v12
	v_exp_f32_e32 v16, v16
	v_and_b32_e32 v13, 0xffff0000, v19
	v_add_f32_e32 v11, 1.0, v11
	v_add_f32_e32 v12, 1.0, v12
	v_add_f32_e32 v10, 1.0, v16
	v_rcp_f32_e32 v11, v11
	v_rcp_f32_e32 v12, v12
	v_mul_f32_e32 v13, 0xbfb8aa3b, v13
	v_rcp_f32_e32 v10, v10
	v_exp_f32_e32 v13, v13
	v_mul_f32_e32 v7, v7, v11
	v_mul_f32_e32 v8, v8, v12
	v_lshlrev_b32_e32 v11, 16, v20
	v_and_b32_e32 v12, 0xffff0000, v20
	v_mul_f32_e32 v6, v6, v10
	v_add_f32_e32 v10, 1.0, v13
	v_mul_f32_e32 v11, 0xbfb8aa3b, v11
	v_mul_f32_e32 v12, 0xbfb8aa3b, v12
	v_rcp_f32_e32 v10, v10
	v_exp_f32_e32 v11, v11
	v_exp_f32_e32 v12, v12
	v_and_b32_e32 v13, 0xffff0000, v21
	v_mul_f32_e32 v9, v9, v10
	v_add_f32_e32 v10, 1.0, v11
	v_add_f32_e32 v11, 1.0, v12
	v_lshlrev_b32_e32 v12, 16, v21
	v_mul_f32_e32 v13, 0xbfb8aa3b, v13
	v_mul_f32_e32 v12, 0xbfb8aa3b, v12
	v_exp_f32_e32 v13, v13
	v_exp_f32_e32 v12, v12
	v_rcp_f32_e32 v10, v10
	v_rcp_f32_e32 v11, v11
	v_add_f32_e32 v13, 1.0, v13
	v_add_f32_e32 v12, 1.0, v12
	v_rcp_f32_e32 v13, v13
	v_rcp_f32_e32 v12, v12
	v_mul_f32_e32 v10, v2, v10
	v_mul_f32_e32 v11, v3, v11
	v_mul_f32_e32 v5, v5, v13
	v_mul_f32_e32 v12, v4, v12
	v_cvt_pk_bf16_f32 v2, v6, v7
	v_cvt_pk_bf16_f32 v3, v8, v9
	v_cvt_pk_bf16_f32 v4, v10, v11
	v_cvt_pk_bf16_f32 v5, v12, v5
	global_store_dwordx4 v[14:15], v[2:5], off offset:256
	s_cbranch_vccnz .LBB0_883
	s_andn2_b64 vcc, exec, s[2:3]
	s_cbranch_vccnz .LBB0_882
	s_barrier
	s_branch .LBB0_882

.LBB0_918:
	v_lshl_or_b32 v146, s53, 8, v156
	v_lshl_add_u32 v148, s22, 8, v1
	v_mov_b64_e32 v[150:151], s[8:9]
	v_ashrrev_i32_e32 v147, 31, v146
	v_mad_i64_i32 v[152:153], s[24:25], v148, s45, v[150:151]
	v_lshlrev_b64 v[146:147], 1, v[146:147]
	v_lshl_add_u64 v[152:153], v[152:153], 0, v[146:147]
	global_load_dwordx4 v[160:163], v[152:153], off
	s_mov_b32 s100, 0x60000
	s_mov_b32 s101, 0
	v_lshl_add_u64 v[238:239], v[152:153], 0, s[100:101]
	global_load_dwordx4 v[234:237], v[238:239], off
	global_load_dwordx4 v[234:237], v[238:239], off offset:256
	v_lshl_add_u64 v[238:239], v[238:239], 0, s[100:101]
	global_load_dwordx4 v[234:237], v[238:239], off
	global_load_dwordx4 v[234:237], v[238:239], off offset:256
	v_lshl_add_u64 v[238:239], v[238:239], 0, s[100:101]
	global_load_dwordx4 v[234:237], v[238:239], off
	global_load_dwordx4 v[234:237], v[238:239], off offset:256
	s_mov_b32 s100, 0x1e0000
	v_lshl_add_u64 v[238:239], v[238:239], 0, s[100:101]
	global_load_dwordx4 v[234:237], v[238:239], off
	global_load_dwordx4 v[234:237], v[238:239], off offset:256
	s_mov_b32 s100, 0x60000
	v_lshl_add_u64 v[238:239], v[238:239], 0, s[100:101]
	global_load_dwordx4 v[234:237], v[238:239], off
	global_load_dwordx4 v[234:237], v[238:239], off offset:256
	v_lshl_add_u64 v[238:239], v[238:239], 0, s[100:101]
	global_load_dwordx4 v[234:237], v[238:239], off
	global_load_dwordx4 v[234:237], v[238:239], off offset:256
	v_lshl_add_u64 v[238:239], v[238:239], 0, s[100:101]
	global_load_dwordx4 v[234:237], v[238:239], off
	global_load_dwordx4 v[234:237], v[238:239], off offset:256
	v_ashrrev_i32_e32 v149, 31, v148
	v_lshlrev_b64 v[172:173], 12, v[148:149]
	v_lshl_add_u64 v[164:165], s[6:7], 0, v[172:173]
	v_lshl_add_u64 v[174:175], v[164:165], 0, v[146:147]
	global_load_dwordx4 v[164:167], v[174:175], off
	global_load_dwordx4 v[168:171], v[152:153], off offset:256
	v_lshl_add_u64 v[172:173], s[2:3], 0, v[172:173]
	v_lshl_add_u64 v[178:179], v[172:173], 0, v[146:147]
	global_load_dwordx4 v[172:175], v[174:175], off offset:256
	v_or_b32_e32 v152, 16, v148
	v_mad_i64_i32 v[176:177], s[24:25], v152, s45, v[150:151]
	v_lshl_add_u64 v[176:177], v[176:177], 0, v[146:147]
	v_ashrrev_i32_e32 v153, 31, v152
	v_lshlrev_b64 v[152:153], 12, v[152:153]
	v_lshl_add_u64 v[180:181], s[6:7], 0, v[152:153]
	s_andn2_b64 vcc, exec, s[4:5]
	s_mov_b64 s[4:5], -1
	s_waitcnt vmcnt(0)
	v_lshlrev_b32_e32 v149, 16, v160
	v_and_b32_e32 v160, 0xffff0000, v160
	v_lshlrev_b32_e32 v182, 16, v161
	v_and_b32_e32 v161, 0xffff0000, v161
	v_lshlrev_b32_e32 v183, 16, v162
	v_and_b32_e32 v162, 0xffff0000, v162
	v_lshlrev_b32_e32 v184, 16, v163
	v_and_b32_e32 v163, 0xffff0000, v163
	v_mul_f32_e32 v149, 0xbfb8aa3b, v149
	v_mul_f32_e32 v160, 0xbfb8aa3b, v160
	v_mul_f32_e32 v182, 0xbfb8aa3b, v182
	v_mul_f32_e32 v161, 0xbfb8aa3b, v161
	v_mul_f32_e32 v183, 0xbfb8aa3b, v183
	v_mul_f32_e32 v162, 0xbfb8aa3b, v162
	v_mul_f32_e32 v184, 0xbfb8aa3b, v184
	v_mul_f32_e32 v163, 0xbfb8aa3b, v163
	v_exp_f32_e32 v149, v149
	v_exp_f32_e32 v160, v160
	v_exp_f32_e32 v182, v182
	v_exp_f32_e32 v161, v161
	v_exp_f32_e32 v183, v183
	v_exp_f32_e32 v162, v162
	v_exp_f32_e32 v184, v184
	v_exp_f32_e32 v163, v163
	v_add_f32_e32 v149, 1.0, v149
	v_add_f32_e32 v160, 1.0, v160
	v_add_f32_e32 v182, 1.0, v182
	v_add_f32_e32 v161, 1.0, v161
	v_add_f32_e32 v183, 1.0, v183
	v_add_f32_e32 v162, 1.0, v162
	v_add_f32_e32 v184, 1.0, v184
	v_add_f32_e32 v163, 1.0, v163
	v_rcp_f32_e32 v149, v149
	v_rcp_f32_e32 v160, v160
	v_rcp_f32_e32 v182, v182
	v_rcp_f32_e32 v161, v161
	v_rcp_f32_e32 v183, v183
	v_rcp_f32_e32 v162, v162
	v_rcp_f32_e32 v184, v184
	v_rcp_f32_e32 v163, v163
	v_lshlrev_b32_e32 v185, 16, v164
	v_and_b32_e32 v164, 0xffff0000, v164
	v_lshlrev_b32_e32 v186, 16, v165
	v_and_b32_e32 v165, 0xffff0000, v165
	v_lshlrev_b32_e32 v187, 16, v166
	v_and_b32_e32 v166, 0xffff0000, v166
	v_lshlrev_b32_e32 v188, 16, v167
	v_and_b32_e32 v167, 0xffff0000, v167
	v_fmac_f32_e32 v185, v126, v149
	v_fmac_f32_e32 v164, v127, v160
	v_fmac_f32_e32 v186, v128, v182
	v_fmac_f32_e32 v165, v129, v161
	v_fmac_f32_e32 v187, v122, v183
	v_fmac_f32_e32 v166, v123, v162
	v_fmac_f32_e32 v188, v124, v184
	v_fmac_f32_e32 v167, v125, v163
	v_cvt_pk_bf16_f32 v122, v185, v164
	v_cvt_pk_bf16_f32 v123, v186, v165
	v_cvt_pk_bf16_f32 v124, v187, v166
	v_cvt_pk_bf16_f32 v125, v188, v167
	global_store_dwordx4 v[178:179], v[122:125], off
	global_load_dwordx4 v[122:125], v[176:177], off
	v_lshlrev_b32_e32 v149, 16, v168
	v_and_b32_e32 v162, 0xffff0000, v168
	v_lshlrev_b32_e32 v163, 16, v169
	v_and_b32_e32 v164, 0xffff0000, v169
	v_lshlrev_b32_e32 v165, 16, v170
	v_and_b32_e32 v166, 0xffff0000, v170
	v_lshlrev_b32_e32 v167, 16, v171
	v_and_b32_e32 v168, 0xffff0000, v171
	v_mul_f32_e32 v149, 0xbfb8aa3b, v149
	v_mul_f32_e32 v162, 0xbfb8aa3b, v162
	v_mul_f32_e32 v163, 0xbfb8aa3b, v163
	v_mul_f32_e32 v164, 0xbfb8aa3b, v164
	v_mul_f32_e32 v165, 0xbfb8aa3b, v165
	v_mul_f32_e32 v166, 0xbfb8aa3b, v166
	v_mul_f32_e32 v167, 0xbfb8aa3b, v167
	v_mul_f32_e32 v168, 0xbfb8aa3b, v168
	v_lshl_add_u64 v[160:161], v[180:181], 0, v[146:147]
	v_exp_f32_e32 v149, v149
	v_exp_f32_e32 v162, v162
	v_exp_f32_e32 v163, v163
	v_exp_f32_e32 v164, v164
	v_exp_f32_e32 v165, v165
	v_exp_f32_e32 v166, v166
	v_exp_f32_e32 v167, v167
	v_exp_f32_e32 v168, v168
	global_load_dwordx4 v[126:129], v[160:161], off
	v_add_f32_e32 v149, 1.0, v149
	v_add_f32_e32 v162, 1.0, v162
	v_add_f32_e32 v163, 1.0, v163
	v_add_f32_e32 v164, 1.0, v164
	v_add_f32_e32 v165, 1.0, v165
	v_add_f32_e32 v166, 1.0, v166
	v_add_f32_e32 v167, 1.0, v167
	v_add_f32_e32 v168, 1.0, v168
	v_rcp_f32_e32 v149, v149
	v_rcp_f32_e32 v162, v162
	v_rcp_f32_e32 v163, v163
	v_rcp_f32_e32 v164, v164
	v_rcp_f32_e32 v165, v165
	v_rcp_f32_e32 v166, v166
	v_rcp_f32_e32 v167, v167
	v_rcp_f32_e32 v168, v168
	v_lshlrev_b32_e32 v169, 16, v172
	v_and_b32_e32 v170, 0xffff0000, v172
	v_lshlrev_b32_e32 v171, 16, v173
	v_and_b32_e32 v172, 0xffff0000, v173
	v_lshlrev_b32_e32 v173, 16, v174
	v_and_b32_e32 v174, 0xffff0000, v174
	v_lshlrev_b32_e32 v180, 16, v175
	v_and_b32_e32 v175, 0xffff0000, v175
	v_fmac_f32_e32 v169, v118, v149
	v_fmac_f32_e32 v170, v119, v162
	v_fmac_f32_e32 v171, v120, v163
	v_fmac_f32_e32 v172, v121, v164
	v_fmac_f32_e32 v173, v114, v165
	v_fmac_f32_e32 v174, v115, v166
	v_fmac_f32_e32 v180, v116, v167
	v_fmac_f32_e32 v175, v117, v168
	v_cvt_pk_bf16_f32 v114, v169, v170
	v_cvt_pk_bf16_f32 v115, v171, v172
	v_cvt_pk_bf16_f32 v116, v173, v174
	v_cvt_pk_bf16_f32 v117, v180, v175
	global_store_dwordx4 v[178:179], v[114:117], off offset:256
	global_load_dwordx4 v[114:117], v[176:177], off offset:256
	s_waitcnt vmcnt(3)
	v_lshlrev_b32_e32 v118, 16, v122
	v_and_b32_e32 v119, 0xffff0000, v122
	v_lshlrev_b32_e32 v120, 16, v123
	v_and_b32_e32 v121, 0xffff0000, v123
	v_mul_f32_e32 v118, 0xbfb8aa3b, v118
	v_mul_f32_e32 v119, 0xbfb8aa3b, v119
	v_mul_f32_e32 v120, 0xbfb8aa3b, v120
	v_mul_f32_e32 v121, 0xbfb8aa3b, v121
	v_exp_f32_e32 v118, v118
	v_exp_f32_e32 v119, v119
	v_exp_f32_e32 v120, v120
	v_exp_f32_e32 v121, v121
	v_add_f32_e32 v118, 1.0, v118
	v_add_f32_e32 v119, 1.0, v119
	v_add_f32_e32 v120, 1.0, v120
	v_add_f32_e32 v121, 1.0, v121
	v_rcp_f32_e32 v149, v118
	v_rcp_f32_e32 v162, v119
	v_rcp_f32_e32 v163, v120
	v_rcp_f32_e32 v164, v121
	global_load_dwordx4 v[118:121], v[160:161], off offset:256
	v_lshlrev_b32_e32 v122, 16, v124
	v_and_b32_e32 v123, 0xffff0000, v124
	v_mul_f32_e32 v122, 0xbfb8aa3b, v122
	v_lshlrev_b32_e32 v124, 16, v125
	v_mul_f32_e32 v123, 0xbfb8aa3b, v123
	v_exp_f32_e32 v122, v122
	v_and_b32_e32 v125, 0xffff0000, v125
	v_mul_f32_e32 v124, 0xbfb8aa3b, v124
	v_exp_f32_e32 v123, v123
	v_mul_f32_e32 v125, 0xbfb8aa3b, v125
	v_exp_f32_e32 v124, v124
	v_exp_f32_e32 v125, v125
	v_add_f32_e32 v122, 1.0, v122
	s_waitcnt vmcnt(3)
	v_lshlrev_b32_e32 v160, 16, v126
	v_add_f32_e32 v123, 1.0, v123
	v_rcp_f32_e32 v122, v122
	v_fmac_f32_e32 v160, v110, v149
	v_and_b32_e32 v110, 0xffff0000, v126
	v_rcp_f32_e32 v123, v123
	v_add_f32_e32 v124, 1.0, v124
	v_fmac_f32_e32 v110, v111, v162
	v_lshlrev_b32_e32 v111, 16, v127
	v_rcp_f32_e32 v124, v124
	v_add_f32_e32 v125, 1.0, v125
	v_fmac_f32_e32 v111, v112, v163
	v_and_b32_e32 v112, 0xffff0000, v127
	v_rcp_f32_e32 v125, v125
	v_fmac_f32_e32 v112, v113, v164
	v_lshlrev_b32_e32 v113, 16, v128
	v_fmac_f32_e32 v113, v106, v122
	v_and_b32_e32 v122, 0xffff0000, v128
	v_fmac_f32_e32 v122, v107, v123
	v_lshlrev_b32_e32 v123, 16, v129
	v_fmac_f32_e32 v123, v108, v124
	v_and_b32_e32 v124, 0xffff0000, v129
	v_cvt_pk_bf16_f32 v106, v160, v110
	v_cvt_pk_bf16_f32 v107, v111, v112
	v_lshl_add_u64 v[110:111], s[2:3], 0, v[152:153]
	v_fmac_f32_e32 v124, v109, v125
	v_cvt_pk_bf16_f32 v108, v113, v122
	v_cvt_pk_bf16_f32 v109, v123, v124
	v_lshl_add_u64 v[122:123], v[110:111], 0, v[146:147]
	global_store_dwordx4 v[122:123], v[106:109], off
	v_or_b32_e32 v110, 32, v148
	s_waitcnt vmcnt(2)
	v_and_b32_e32 v112, 0xffff0000, v114
	v_lshlrev_b32_e32 v106, 16, v114
	v_mul_f32_e32 v106, 0xbfb8aa3b, v106
	v_exp_f32_e32 v111, v106
	v_mad_i64_i32 v[106:107], s[24:25], v110, s45, v[150:151]
	v_lshl_add_u64 v[124:125], v[106:107], 0, v[146:147]
	v_mul_f32_e32 v112, 0xbfb8aa3b, v112
	global_load_dwordx4 v[106:109], v[124:125], off
	v_exp_f32_e32 v112, v112
	v_add_f32_e32 v111, 1.0, v111
	v_rcp_f32_e32 v126, v111
	v_and_b32_e32 v113, 0xffff0000, v115
	v_add_f32_e32 v111, 1.0, v112
	v_lshlrev_b32_e32 v112, 16, v115
	v_mul_f32_e32 v112, 0xbfb8aa3b, v112
	v_exp_f32_e32 v112, v112
	v_mul_f32_e32 v113, 0xbfb8aa3b, v113
	v_rcp_f32_e32 v127, v111
	v_exp_f32_e32 v113, v113
	v_add_f32_e32 v111, 1.0, v112
	v_lshlrev_b32_e32 v112, 16, v116
	v_mul_f32_e32 v112, 0xbfb8aa3b, v112
	v_exp_f32_e32 v112, v112
	v_rcp_f32_e32 v128, v111
	v_add_f32_e32 v111, 1.0, v113
	v_and_b32_e32 v113, 0xffff0000, v116
	v_mul_f32_e32 v113, 0xbfb8aa3b, v113
	v_rcp_f32_e32 v129, v111
	v_add_f32_e32 v111, 1.0, v112
	v_lshlrev_b32_e32 v112, 16, v117
	v_exp_f32_e32 v113, v113
	v_mul_f32_e32 v112, 0xbfb8aa3b, v112
	v_exp_f32_e32 v112, v112
	v_rcp_f32_e32 v149, v111
	v_add_f32_e32 v111, 1.0, v113
	v_and_b32_e32 v113, 0xffff0000, v117
	v_mul_f32_e32 v113, 0xbfb8aa3b, v113
	v_rcp_f32_e32 v152, v111
	v_add_f32_e32 v111, 1.0, v112
	v_exp_f32_e32 v113, v113
	v_rcp_f32_e32 v153, v111
	v_ashrrev_i32_e32 v111, 31, v110
	v_lshlrev_b64 v[114:115], 12, v[110:111]
	v_lshl_add_u64 v[110:111], s[6:7], 0, v[114:115]
	v_lshl_add_u64 v[116:117], v[110:111], 0, v[146:147]
	v_add_f32_e32 v160, 1.0, v113
	global_load_dwordx4 v[110:113], v[116:117], off
	s_waitcnt vmcnt(3)
	v_lshlrev_b32_e32 v161, 16, v118
	v_rcp_f32_e32 v160, v160
	v_fmac_f32_e32 v161, v102, v126
	v_and_b32_e32 v102, 0xffff0000, v118
	v_fmac_f32_e32 v102, v103, v127
	v_lshlrev_b32_e32 v103, 16, v119
	v_fmac_f32_e32 v103, v104, v128
	v_and_b32_e32 v104, 0xffff0000, v119
	v_fmac_f32_e32 v104, v105, v129
	v_lshlrev_b32_e32 v105, 16, v120
	v_and_b32_e32 v118, 0xffff0000, v120
	v_lshlrev_b32_e32 v119, 16, v121
	v_and_b32_e32 v120, 0xffff0000, v121
	v_fmac_f32_e32 v105, v98, v149
	v_fmac_f32_e32 v118, v99, v152
	v_fmac_f32_e32 v119, v100, v153
	v_fmac_f32_e32 v120, v101, v160
	v_cvt_pk_bf16_f32 v98, v161, v102
	v_cvt_pk_bf16_f32 v99, v103, v104
	v_cvt_pk_bf16_f32 v100, v105, v118
	v_cvt_pk_bf16_f32 v101, v119, v120
	global_store_dwordx4 v[122:123], v[98:101], off offset:256
	global_load_dwordx4 v[98:101], v[124:125], off offset:256
	s_waitcnt vmcnt(3)
	v_lshlrev_b32_e32 v102, 16, v106
	v_mul_f32_e32 v102, 0xbfb8aa3b, v102
	v_and_b32_e32 v103, 0xffff0000, v106
	v_exp_f32_e32 v102, v102
	v_mul_f32_e32 v103, 0xbfb8aa3b, v103
	v_exp_f32_e32 v103, v103
	v_and_b32_e32 v104, 0xffff0000, v107
	v_add_f32_e32 v102, 1.0, v102
	v_rcp_f32_e32 v106, v102
	v_add_f32_e32 v102, 1.0, v103
	v_lshlrev_b32_e32 v103, 16, v107
	v_mul_f32_e32 v103, 0xbfb8aa3b, v103
	v_exp_f32_e32 v103, v103
	v_mul_f32_e32 v104, 0xbfb8aa3b, v104
	v_rcp_f32_e32 v107, v102
	v_exp_f32_e32 v104, v104
	v_add_f32_e32 v102, 1.0, v103
	v_lshlrev_b32_e32 v103, 16, v108
	v_mul_f32_e32 v103, 0xbfb8aa3b, v103
	v_exp_f32_e32 v103, v103
	v_rcp_f32_e32 v118, v102
	v_add_f32_e32 v102, 1.0, v104
	v_and_b32_e32 v104, 0xffff0000, v108
	v_mul_f32_e32 v104, 0xbfb8aa3b, v104
	v_rcp_f32_e32 v108, v102
	v_add_f32_e32 v102, 1.0, v103
	v_exp_f32_e32 v104, v104
	v_rcp_f32_e32 v119, v102
	v_lshlrev_b32_e32 v102, 16, v109
	v_mul_f32_e32 v102, 0xbfb8aa3b, v102
	v_exp_f32_e32 v121, v102
	v_and_b32_e32 v102, 0xffff0000, v109
	v_mul_f32_e32 v102, 0xbfb8aa3b, v102
	v_add_f32_e32 v120, 1.0, v104
	v_exp_f32_e32 v109, v102
	global_load_dwordx4 v[102:105], v[116:117], off offset:256
	v_rcp_f32_e32 v116, v120
	v_add_f32_e32 v117, 1.0, v121
	v_rcp_f32_e32 v117, v117
	s_waitcnt vmcnt(3)
	v_lshlrev_b32_e32 v120, 16, v110
	v_add_f32_e32 v109, 1.0, v109
	v_fmac_f32_e32 v120, v94, v106
	v_and_b32_e32 v94, 0xffff0000, v110
	v_rcp_f32_e32 v109, v109
	v_fmac_f32_e32 v94, v95, v107
	v_lshlrev_b32_e32 v95, 16, v111
	v_fmac_f32_e32 v95, v96, v118
	v_and_b32_e32 v96, 0xffff0000, v111
	v_fmac_f32_e32 v96, v97, v108
	v_lshlrev_b32_e32 v97, 16, v112
	v_and_b32_e32 v106, 0xffff0000, v112
	v_lshlrev_b32_e32 v107, 16, v113
	v_fmac_f32_e32 v97, v90, v119
	v_fmac_f32_e32 v106, v91, v116
	v_fmac_f32_e32 v107, v92, v117
	v_and_b32_e32 v108, 0xffff0000, v113
	v_cvt_pk_bf16_f32 v90, v120, v94
	v_cvt_pk_bf16_f32 v91, v95, v96
	v_lshl_add_u64 v[94:95], s[2:3], 0, v[114:115]
	v_fmac_f32_e32 v108, v93, v109
	v_cvt_pk_bf16_f32 v92, v97, v106
	v_cvt_pk_bf16_f32 v93, v107, v108
	v_lshl_add_u64 v[106:107], v[94:95], 0, v[146:147]
	global_store_dwordx4 v[106:107], v[90:93], off
	v_or_b32_e32 v94, 48, v148
	s_waitcnt vmcnt(2)
	v_and_b32_e32 v96, 0xffff0000, v98
	v_lshlrev_b32_e32 v90, 16, v98
	v_mul_f32_e32 v90, 0xbfb8aa3b, v90
	v_exp_f32_e32 v95, v90
	v_mad_i64_i32 v[90:91], s[24:25], v94, s45, v[150:151]
	v_lshl_add_u64 v[108:109], v[90:91], 0, v[146:147]
	global_load_dwordx4 v[90:93], v[108:109], off
	v_mul_f32_e32 v96, 0xbfb8aa3b, v96
	v_exp_f32_e32 v96, v96
	v_add_f32_e32 v95, 1.0, v95
	v_rcp_f32_e32 v110, v95
	v_and_b32_e32 v97, 0xffff0000, v99
	v_add_f32_e32 v95, 1.0, v96
	v_lshlrev_b32_e32 v96, 16, v99
	v_mul_f32_e32 v96, 0xbfb8aa3b, v96
	v_exp_f32_e32 v96, v96
	v_mul_f32_e32 v97, 0xbfb8aa3b, v97
	v_rcp_f32_e32 v111, v95
	v_exp_f32_e32 v97, v97
	v_add_f32_e32 v95, 1.0, v96
	v_lshlrev_b32_e32 v96, 16, v100
	v_mul_f32_e32 v96, 0xbfb8aa3b, v96
	v_exp_f32_e32 v96, v96
	v_rcp_f32_e32 v112, v95
	v_add_f32_e32 v95, 1.0, v97
	v_and_b32_e32 v97, 0xffff0000, v100
	v_mul_f32_e32 v97, 0xbfb8aa3b, v97
	v_rcp_f32_e32 v113, v95
	v_add_f32_e32 v95, 1.0, v96
	v_lshlrev_b32_e32 v96, 16, v101
	v_exp_f32_e32 v97, v97
	v_mul_f32_e32 v96, 0xbfb8aa3b, v96
	v_exp_f32_e32 v96, v96
	v_rcp_f32_e32 v114, v95
	v_add_f32_e32 v95, 1.0, v97
	v_and_b32_e32 v97, 0xffff0000, v101
	v_mul_f32_e32 v97, 0xbfb8aa3b, v97
	v_rcp_f32_e32 v115, v95
	v_add_f32_e32 v95, 1.0, v96
	v_exp_f32_e32 v97, v97
	v_rcp_f32_e32 v116, v95
	v_ashrrev_i32_e32 v95, 31, v94
	v_lshlrev_b64 v[98:99], 12, v[94:95]
	v_lshl_add_u64 v[94:95], s[6:7], 0, v[98:99]
	v_lshl_add_u64 v[100:101], v[94:95], 0, v[146:147]
	v_add_f32_e32 v117, 1.0, v97
	global_load_dwordx4 v[94:97], v[100:101], off
	v_rcp_f32_e32 v117, v117
	s_waitcnt vmcnt(3)
	v_lshlrev_b32_e32 v118, 16, v102
	v_fmac_f32_e32 v118, v86, v110
	v_and_b32_e32 v86, 0xffff0000, v102
	v_fmac_f32_e32 v86, v87, v111
	v_lshlrev_b32_e32 v87, 16, v103
	v_fmac_f32_e32 v87, v88, v112
	v_and_b32_e32 v88, 0xffff0000, v103
	v_fmac_f32_e32 v88, v89, v113
	v_lshlrev_b32_e32 v89, 16, v104
	v_and_b32_e32 v102, 0xffff0000, v104
	v_lshlrev_b32_e32 v103, 16, v105
	v_and_b32_e32 v104, 0xffff0000, v105
	v_fmac_f32_e32 v89, v82, v114
	v_fmac_f32_e32 v102, v83, v115
	v_fmac_f32_e32 v103, v84, v116
	v_fmac_f32_e32 v104, v85, v117
	v_cvt_pk_bf16_f32 v82, v118, v86
	v_cvt_pk_bf16_f32 v83, v87, v88
	v_cvt_pk_bf16_f32 v84, v89, v102
	v_cvt_pk_bf16_f32 v85, v103, v104
	global_store_dwordx4 v[106:107], v[82:85], off offset:256
	global_load_dwordx4 v[82:85], v[108:109], off offset:256
	s_waitcnt vmcnt(3)
	v_lshlrev_b32_e32 v86, 16, v90
	v_mul_f32_e32 v86, 0xbfb8aa3b, v86
	v_and_b32_e32 v87, 0xffff0000, v90
	v_exp_f32_e32 v86, v86
	v_mul_f32_e32 v87, 0xbfb8aa3b, v87
	v_exp_f32_e32 v87, v87
	v_and_b32_e32 v88, 0xffff0000, v91
	v_add_f32_e32 v86, 1.0, v86
	v_rcp_f32_e32 v90, v86
	v_add_f32_e32 v86, 1.0, v87
	v_lshlrev_b32_e32 v87, 16, v91
	v_mul_f32_e32 v87, 0xbfb8aa3b, v87
	v_exp_f32_e32 v87, v87
	v_mul_f32_e32 v88, 0xbfb8aa3b, v88
	v_rcp_f32_e32 v91, v86
	v_exp_f32_e32 v88, v88
	v_add_f32_e32 v86, 1.0, v87
	v_lshlrev_b32_e32 v87, 16, v92
	v_mul_f32_e32 v87, 0xbfb8aa3b, v87
	v_exp_f32_e32 v87, v87
	v_rcp_f32_e32 v102, v86
	v_add_f32_e32 v86, 1.0, v88
	v_and_b32_e32 v88, 0xffff0000, v92
	v_mul_f32_e32 v88, 0xbfb8aa3b, v88
	v_rcp_f32_e32 v92, v86
	v_add_f32_e32 v86, 1.0, v87
	v_exp_f32_e32 v88, v88
	v_rcp_f32_e32 v103, v86
	v_lshlrev_b32_e32 v86, 16, v93
	v_mul_f32_e32 v86, 0xbfb8aa3b, v86
	v_exp_f32_e32 v105, v86
	v_and_b32_e32 v86, 0xffff0000, v93
	v_mul_f32_e32 v86, 0xbfb8aa3b, v86
	v_add_f32_e32 v104, 1.0, v88
	v_exp_f32_e32 v93, v86
	global_load_dwordx4 v[86:89], v[100:101], off offset:256
	v_rcp_f32_e32 v100, v104
	v_add_f32_e32 v101, 1.0, v105
	v_rcp_f32_e32 v101, v101
	v_add_f32_e32 v93, 1.0, v93
	s_waitcnt vmcnt(3)
	v_lshlrev_b32_e32 v104, 16, v94
	v_fmac_f32_e32 v104, v78, v90
	v_and_b32_e32 v78, 0xffff0000, v94
	v_rcp_f32_e32 v93, v93
	v_fmac_f32_e32 v78, v79, v91
	v_lshlrev_b32_e32 v79, 16, v95
	v_fmac_f32_e32 v79, v80, v102
	v_and_b32_e32 v80, 0xffff0000, v95
	v_fmac_f32_e32 v80, v81, v92
	v_lshlrev_b32_e32 v81, 16, v96
	v_and_b32_e32 v90, 0xffff0000, v96
	v_lshlrev_b32_e32 v91, 16, v97
	v_fmac_f32_e32 v81, v74, v103
	v_fmac_f32_e32 v90, v75, v100
	v_fmac_f32_e32 v91, v76, v101
	v_and_b32_e32 v92, 0xffff0000, v97
	v_cvt_pk_bf16_f32 v74, v104, v78
	v_cvt_pk_bf16_f32 v75, v79, v80
	v_lshl_add_u64 v[78:79], s[2:3], 0, v[98:99]
	v_fmac_f32_e32 v92, v77, v93
	v_cvt_pk_bf16_f32 v76, v81, v90
	v_cvt_pk_bf16_f32 v77, v91, v92
	v_lshl_add_u64 v[90:91], v[78:79], 0, v[146:147]
	global_store_dwordx4 v[90:91], v[74:77], off
	v_add_u32_e32 v78, 0x80, v148
	s_waitcnt vmcnt(2)
	v_and_b32_e32 v80, 0xffff0000, v82
	v_lshlrev_b32_e32 v74, 16, v82
	v_mul_f32_e32 v74, 0xbfb8aa3b, v74
	v_exp_f32_e32 v79, v74
	v_mad_i64_i32 v[74:75], s[24:25], v78, s45, v[150:151]
	v_lshl_add_u64 v[92:93], v[74:75], 0, v[146:147]
	v_mul_f32_e32 v80, 0xbfb8aa3b, v80
	global_load_dwordx4 v[74:77], v[92:93], off
	v_exp_f32_e32 v80, v80
	v_add_f32_e32 v79, 1.0, v79
	v_rcp_f32_e32 v94, v79
	v_and_b32_e32 v81, 0xffff0000, v83
	v_add_f32_e32 v79, 1.0, v80
	v_lshlrev_b32_e32 v80, 16, v83
	v_mul_f32_e32 v80, 0xbfb8aa3b, v80
	v_exp_f32_e32 v80, v80
	v_mul_f32_e32 v81, 0xbfb8aa3b, v81
	v_rcp_f32_e32 v95, v79
	v_exp_f32_e32 v81, v81
	v_add_f32_e32 v79, 1.0, v80
	v_lshlrev_b32_e32 v80, 16, v84
	v_mul_f32_e32 v80, 0xbfb8aa3b, v80
	v_exp_f32_e32 v80, v80
	v_rcp_f32_e32 v96, v79
	v_add_f32_e32 v79, 1.0, v81
	v_and_b32_e32 v81, 0xffff0000, v84
	v_mul_f32_e32 v81, 0xbfb8aa3b, v81
	v_rcp_f32_e32 v97, v79
	v_add_f32_e32 v79, 1.0, v80
	v_lshlrev_b32_e32 v80, 16, v85
	v_exp_f32_e32 v81, v81
	v_mul_f32_e32 v80, 0xbfb8aa3b, v80
	v_exp_f32_e32 v80, v80
	v_rcp_f32_e32 v98, v79
	v_add_f32_e32 v79, 1.0, v81
	v_and_b32_e32 v81, 0xffff0000, v85
	v_mul_f32_e32 v81, 0xbfb8aa3b, v81
	v_rcp_f32_e32 v99, v79
	v_add_f32_e32 v79, 1.0, v80
	v_exp_f32_e32 v81, v81
	v_rcp_f32_e32 v100, v79
	v_ashrrev_i32_e32 v79, 31, v78
	v_lshlrev_b64 v[82:83], 12, v[78:79]
	v_lshl_add_u64 v[78:79], s[6:7], 0, v[82:83]
	v_lshl_add_u64 v[84:85], v[78:79], 0, v[146:147]
	v_add_f32_e32 v101, 1.0, v81
	global_load_dwordx4 v[78:81], v[84:85], off
	v_rcp_f32_e32 v101, v101
	s_waitcnt vmcnt(3)
	v_lshlrev_b32_e32 v102, 16, v86
	v_fmac_f32_e32 v102, v70, v94
	v_and_b32_e32 v70, 0xffff0000, v86
	v_fmac_f32_e32 v70, v71, v95
	v_lshlrev_b32_e32 v71, 16, v87
	v_fmac_f32_e32 v71, v72, v96
	v_and_b32_e32 v72, 0xffff0000, v87
	v_fmac_f32_e32 v72, v73, v97
	v_lshlrev_b32_e32 v73, 16, v88
	v_and_b32_e32 v86, 0xffff0000, v88
	v_lshlrev_b32_e32 v87, 16, v89
	v_and_b32_e32 v88, 0xffff0000, v89
	v_fmac_f32_e32 v73, v66, v98
	v_fmac_f32_e32 v86, v67, v99
	v_fmac_f32_e32 v87, v68, v100
	v_fmac_f32_e32 v88, v69, v101
	v_cvt_pk_bf16_f32 v66, v102, v70
	v_cvt_pk_bf16_f32 v67, v71, v72
	v_cvt_pk_bf16_f32 v68, v73, v86
	v_cvt_pk_bf16_f32 v69, v87, v88
	global_store_dwordx4 v[90:91], v[66:69], off offset:256
	global_load_dwordx4 v[66:69], v[92:93], off offset:256
	s_waitcnt vmcnt(3)
	v_lshlrev_b32_e32 v70, 16, v74
	v_mul_f32_e32 v70, 0xbfb8aa3b, v70
	v_and_b32_e32 v71, 0xffff0000, v74
	v_exp_f32_e32 v70, v70
	v_mul_f32_e32 v71, 0xbfb8aa3b, v71
	v_exp_f32_e32 v71, v71
	v_and_b32_e32 v72, 0xffff0000, v75
	v_add_f32_e32 v70, 1.0, v70
	v_rcp_f32_e32 v74, v70
	v_add_f32_e32 v70, 1.0, v71
	v_lshlrev_b32_e32 v71, 16, v75
	v_mul_f32_e32 v71, 0xbfb8aa3b, v71
	v_exp_f32_e32 v71, v71
	v_mul_f32_e32 v72, 0xbfb8aa3b, v72
	v_rcp_f32_e32 v75, v70
	v_exp_f32_e32 v72, v72
	v_add_f32_e32 v70, 1.0, v71
	v_lshlrev_b32_e32 v71, 16, v76
	v_mul_f32_e32 v71, 0xbfb8aa3b, v71
	v_exp_f32_e32 v71, v71
	v_rcp_f32_e32 v86, v70
	v_add_f32_e32 v70, 1.0, v72
	v_and_b32_e32 v72, 0xffff0000, v76
	v_mul_f32_e32 v72, 0xbfb8aa3b, v72
	v_rcp_f32_e32 v76, v70
	v_add_f32_e32 v70, 1.0, v71
	v_exp_f32_e32 v72, v72
	v_rcp_f32_e32 v87, v70
	v_lshlrev_b32_e32 v70, 16, v77
	v_mul_f32_e32 v70, 0xbfb8aa3b, v70
	v_exp_f32_e32 v89, v70
	v_and_b32_e32 v70, 0xffff0000, v77
	v_mul_f32_e32 v70, 0xbfb8aa3b, v70
	v_add_f32_e32 v88, 1.0, v72
	v_exp_f32_e32 v77, v70
	global_load_dwordx4 v[70:73], v[84:85], off offset:256
	v_rcp_f32_e32 v84, v88
	v_add_f32_e32 v85, 1.0, v89
	v_rcp_f32_e32 v85, v85
	s_waitcnt vmcnt(3)
	v_lshlrev_b32_e32 v88, 16, v78
	v_add_f32_e32 v77, 1.0, v77
	v_fmac_f32_e32 v88, v62, v74
	v_and_b32_e32 v62, 0xffff0000, v78
	v_rcp_f32_e32 v77, v77
	v_fmac_f32_e32 v62, v63, v75
	v_lshlrev_b32_e32 v63, 16, v79
	v_fmac_f32_e32 v63, v64, v86
	v_and_b32_e32 v64, 0xffff0000, v79
	v_fmac_f32_e32 v64, v65, v76
	v_lshlrev_b32_e32 v65, 16, v80
	v_and_b32_e32 v74, 0xffff0000, v80
	v_lshlrev_b32_e32 v75, 16, v81
	v_fmac_f32_e32 v65, v58, v87
	v_fmac_f32_e32 v74, v59, v84
	v_fmac_f32_e32 v75, v60, v85
	v_and_b32_e32 v76, 0xffff0000, v81
	v_cvt_pk_bf16_f32 v58, v88, v62
	v_cvt_pk_bf16_f32 v59, v63, v64
	v_lshl_add_u64 v[62:63], s[2:3], 0, v[82:83]
	v_fmac_f32_e32 v76, v61, v77
	v_cvt_pk_bf16_f32 v60, v65, v74
	v_cvt_pk_bf16_f32 v61, v75, v76
	v_lshl_add_u64 v[74:75], v[62:63], 0, v[146:147]
	global_store_dwordx4 v[74:75], v[58:61], off
	v_add_u32_e32 v62, 0x90, v148
	s_waitcnt vmcnt(2)
	v_and_b32_e32 v64, 0xffff0000, v66
	v_lshlrev_b32_e32 v58, 16, v66
	v_mul_f32_e32 v58, 0xbfb8aa3b, v58
	v_exp_f32_e32 v63, v58
	v_mad_i64_i32 v[58:59], s[24:25], v62, s45, v[150:151]
	v_lshl_add_u64 v[76:77], v[58:59], 0, v[146:147]
	global_load_dwordx4 v[58:61], v[76:77], off
	v_mul_f32_e32 v64, 0xbfb8aa3b, v64
	v_exp_f32_e32 v64, v64
	v_add_f32_e32 v63, 1.0, v63
	v_rcp_f32_e32 v78, v63
	v_and_b32_e32 v65, 0xffff0000, v67
	v_add_f32_e32 v63, 1.0, v64
	v_lshlrev_b32_e32 v64, 16, v67
	v_mul_f32_e32 v64, 0xbfb8aa3b, v64
	v_exp_f32_e32 v64, v64
	v_mul_f32_e32 v65, 0xbfb8aa3b, v65
	v_rcp_f32_e32 v79, v63
	v_exp_f32_e32 v65, v65
	v_add_f32_e32 v63, 1.0, v64
	v_lshlrev_b32_e32 v64, 16, v68
	v_mul_f32_e32 v64, 0xbfb8aa3b, v64
	v_exp_f32_e32 v64, v64
	v_rcp_f32_e32 v80, v63
	v_add_f32_e32 v63, 1.0, v65
	v_and_b32_e32 v65, 0xffff0000, v68
	v_mul_f32_e32 v65, 0xbfb8aa3b, v65
	v_rcp_f32_e32 v81, v63
	v_add_f32_e32 v63, 1.0, v64
	v_lshlrev_b32_e32 v64, 16, v69
	v_exp_f32_e32 v65, v65
	v_mul_f32_e32 v64, 0xbfb8aa3b, v64
	v_exp_f32_e32 v64, v64
	v_rcp_f32_e32 v82, v63
	v_add_f32_e32 v63, 1.0, v65
	v_and_b32_e32 v65, 0xffff0000, v69
	v_mul_f32_e32 v65, 0xbfb8aa3b, v65
	v_rcp_f32_e32 v83, v63
	v_add_f32_e32 v63, 1.0, v64
	v_exp_f32_e32 v65, v65
	v_rcp_f32_e32 v84, v63
	v_ashrrev_i32_e32 v63, 31, v62
	v_lshlrev_b64 v[66:67], 12, v[62:63]
	v_lshl_add_u64 v[62:63], s[6:7], 0, v[66:67]
	v_lshl_add_u64 v[68:69], v[62:63], 0, v[146:147]
	v_add_f32_e32 v85, 1.0, v65
	global_load_dwordx4 v[62:65], v[68:69], off
	v_rcp_f32_e32 v85, v85
	s_waitcnt vmcnt(3)
	v_lshlrev_b32_e32 v86, 16, v70
	v_fmac_f32_e32 v86, v54, v78
	v_and_b32_e32 v54, 0xffff0000, v70
	v_fmac_f32_e32 v54, v55, v79
	v_lshlrev_b32_e32 v55, 16, v71
	v_fmac_f32_e32 v55, v56, v80
	v_and_b32_e32 v56, 0xffff0000, v71
	v_fmac_f32_e32 v56, v57, v81
	v_lshlrev_b32_e32 v57, 16, v72
	v_and_b32_e32 v70, 0xffff0000, v72
	v_lshlrev_b32_e32 v71, 16, v73
	v_and_b32_e32 v72, 0xffff0000, v73
	v_fmac_f32_e32 v57, v50, v82
	v_fmac_f32_e32 v70, v51, v83
	v_fmac_f32_e32 v71, v52, v84
	v_fmac_f32_e32 v72, v53, v85
	v_cvt_pk_bf16_f32 v50, v86, v54
	v_cvt_pk_bf16_f32 v51, v55, v56
	v_cvt_pk_bf16_f32 v52, v57, v70
	v_cvt_pk_bf16_f32 v53, v71, v72
	global_store_dwordx4 v[74:75], v[50:53], off offset:256
	global_load_dwordx4 v[50:53], v[76:77], off offset:256
	s_waitcnt vmcnt(3)
	v_lshlrev_b32_e32 v54, 16, v58
	v_mul_f32_e32 v54, 0xbfb8aa3b, v54
	v_and_b32_e32 v55, 0xffff0000, v58
	v_exp_f32_e32 v54, v54
	v_mul_f32_e32 v55, 0xbfb8aa3b, v55
	v_exp_f32_e32 v55, v55
	v_and_b32_e32 v56, 0xffff0000, v59
	v_add_f32_e32 v54, 1.0, v54
	v_rcp_f32_e32 v58, v54
	v_add_f32_e32 v54, 1.0, v55
	v_lshlrev_b32_e32 v55, 16, v59
	v_mul_f32_e32 v55, 0xbfb8aa3b, v55
	v_exp_f32_e32 v55, v55
	v_mul_f32_e32 v56, 0xbfb8aa3b, v56
	v_rcp_f32_e32 v59, v54
	v_exp_f32_e32 v56, v56
	v_add_f32_e32 v54, 1.0, v55
	v_lshlrev_b32_e32 v55, 16, v60
	v_mul_f32_e32 v55, 0xbfb8aa3b, v55
	v_exp_f32_e32 v55, v55
	v_rcp_f32_e32 v70, v54
	v_add_f32_e32 v54, 1.0, v56
	v_and_b32_e32 v56, 0xffff0000, v60
	v_mul_f32_e32 v56, 0xbfb8aa3b, v56
	v_rcp_f32_e32 v60, v54
	v_add_f32_e32 v54, 1.0, v55
	v_exp_f32_e32 v56, v56
	v_rcp_f32_e32 v71, v54
	v_lshlrev_b32_e32 v54, 16, v61
	v_mul_f32_e32 v54, 0xbfb8aa3b, v54
	v_exp_f32_e32 v73, v54
	v_and_b32_e32 v54, 0xffff0000, v61
	v_mul_f32_e32 v54, 0xbfb8aa3b, v54
	v_add_f32_e32 v72, 1.0, v56
	v_exp_f32_e32 v61, v54
	global_load_dwordx4 v[54:57], v[68:69], off offset:256
	v_rcp_f32_e32 v68, v72
	v_add_f32_e32 v69, 1.0, v73
	v_rcp_f32_e32 v69, v69
	v_add_f32_e32 v61, 1.0, v61
	s_waitcnt vmcnt(3)
	v_lshlrev_b32_e32 v72, 16, v62
	v_fmac_f32_e32 v72, v46, v58
	v_and_b32_e32 v46, 0xffff0000, v62
	v_rcp_f32_e32 v61, v61
	v_fmac_f32_e32 v46, v47, v59
	v_lshlrev_b32_e32 v47, 16, v63
	v_fmac_f32_e32 v47, v48, v70
	v_and_b32_e32 v48, 0xffff0000, v63
	v_fmac_f32_e32 v48, v49, v60
	v_lshlrev_b32_e32 v49, 16, v64
	v_and_b32_e32 v58, 0xffff0000, v64
	v_lshlrev_b32_e32 v59, 16, v65
	v_fmac_f32_e32 v49, v42, v71
	v_fmac_f32_e32 v58, v43, v68
	v_fmac_f32_e32 v59, v44, v69
	v_and_b32_e32 v60, 0xffff0000, v65
	v_cvt_pk_bf16_f32 v42, v72, v46
	v_cvt_pk_bf16_f32 v43, v47, v48
	v_lshl_add_u64 v[46:47], s[2:3], 0, v[66:67]
	v_fmac_f32_e32 v60, v45, v61
	v_cvt_pk_bf16_f32 v44, v49, v58
	v_cvt_pk_bf16_f32 v45, v59, v60
	v_lshl_add_u64 v[58:59], v[46:47], 0, v[146:147]
	global_store_dwordx4 v[58:59], v[42:45], off
	v_add_u32_e32 v46, 0xa0, v148
	s_waitcnt vmcnt(2)
	v_and_b32_e32 v48, 0xffff0000, v50
	v_lshlrev_b32_e32 v42, 16, v50
	v_mul_f32_e32 v42, 0xbfb8aa3b, v42
	v_exp_f32_e32 v47, v42
	v_mad_i64_i32 v[42:43], s[24:25], v46, s45, v[150:151]
	v_lshl_add_u64 v[60:61], v[42:43], 0, v[146:147]
	v_mul_f32_e32 v48, 0xbfb8aa3b, v48
	global_load_dwordx4 v[42:45], v[60:61], off
	v_exp_f32_e32 v48, v48
	v_add_f32_e32 v47, 1.0, v47
	v_rcp_f32_e32 v62, v47
	v_and_b32_e32 v49, 0xffff0000, v51
	v_add_f32_e32 v47, 1.0, v48
	v_lshlrev_b32_e32 v48, 16, v51
	v_mul_f32_e32 v48, 0xbfb8aa3b, v48
	v_exp_f32_e32 v48, v48
	v_mul_f32_e32 v49, 0xbfb8aa3b, v49
	v_rcp_f32_e32 v63, v47
	v_exp_f32_e32 v49, v49
	v_add_f32_e32 v47, 1.0, v48
	v_lshlrev_b32_e32 v48, 16, v52
	v_mul_f32_e32 v48, 0xbfb8aa3b, v48
	v_exp_f32_e32 v48, v48
	v_rcp_f32_e32 v64, v47
	v_add_f32_e32 v47, 1.0, v49
	v_and_b32_e32 v49, 0xffff0000, v52
	v_mul_f32_e32 v49, 0xbfb8aa3b, v49
	v_rcp_f32_e32 v65, v47
	v_add_f32_e32 v47, 1.0, v48
	v_lshlrev_b32_e32 v48, 16, v53
	v_exp_f32_e32 v49, v49
	v_mul_f32_e32 v48, 0xbfb8aa3b, v48
	v_exp_f32_e32 v48, v48
	v_rcp_f32_e32 v66, v47
	v_add_f32_e32 v47, 1.0, v49
	v_and_b32_e32 v49, 0xffff0000, v53
	v_mul_f32_e32 v49, 0xbfb8aa3b, v49
	v_rcp_f32_e32 v67, v47
	v_add_f32_e32 v47, 1.0, v48
	v_exp_f32_e32 v49, v49
	v_rcp_f32_e32 v68, v47
	v_ashrrev_i32_e32 v47, 31, v46
	v_lshlrev_b64 v[50:51], 12, v[46:47]
	v_lshl_add_u64 v[46:47], s[6:7], 0, v[50:51]
	v_lshl_add_u64 v[52:53], v[46:47], 0, v[146:147]
	v_add_f32_e32 v69, 1.0, v49
	global_load_dwordx4 v[46:49], v[52:53], off
	v_rcp_f32_e32 v69, v69
	s_waitcnt vmcnt(3)
	v_lshlrev_b32_e32 v70, 16, v54
	v_fmac_f32_e32 v70, v38, v62
	v_and_b32_e32 v38, 0xffff0000, v54
	v_fmac_f32_e32 v38, v39, v63
	v_lshlrev_b32_e32 v39, 16, v55
	v_fmac_f32_e32 v39, v40, v64
	v_and_b32_e32 v40, 0xffff0000, v55
	v_fmac_f32_e32 v40, v41, v65
	v_lshlrev_b32_e32 v41, 16, v56
	v_and_b32_e32 v54, 0xffff0000, v56
	v_lshlrev_b32_e32 v55, 16, v57
	v_and_b32_e32 v56, 0xffff0000, v57
	v_fmac_f32_e32 v41, v34, v66
	v_fmac_f32_e32 v54, v35, v67
	v_fmac_f32_e32 v55, v36, v68
	v_fmac_f32_e32 v56, v37, v69
	v_cvt_pk_bf16_f32 v34, v70, v38
	v_cvt_pk_bf16_f32 v35, v39, v40
	v_cvt_pk_bf16_f32 v36, v41, v54
	v_cvt_pk_bf16_f32 v37, v55, v56
	global_store_dwordx4 v[58:59], v[34:37], off offset:256
	global_load_dwordx4 v[34:37], v[60:61], off offset:256
	s_waitcnt vmcnt(3)
	v_lshlrev_b32_e32 v38, 16, v42
	v_mul_f32_e32 v38, 0xbfb8aa3b, v38
	v_and_b32_e32 v39, 0xffff0000, v42
	v_exp_f32_e32 v38, v38
	v_mul_f32_e32 v39, 0xbfb8aa3b, v39
	v_exp_f32_e32 v39, v39
	v_and_b32_e32 v40, 0xffff0000, v43
	v_add_f32_e32 v38, 1.0, v38
	v_rcp_f32_e32 v42, v38
	v_add_f32_e32 v38, 1.0, v39
	v_lshlrev_b32_e32 v39, 16, v43
	v_mul_f32_e32 v39, 0xbfb8aa3b, v39
	v_exp_f32_e32 v39, v39
	v_mul_f32_e32 v40, 0xbfb8aa3b, v40
	v_rcp_f32_e32 v43, v38
	v_exp_f32_e32 v40, v40
	v_add_f32_e32 v38, 1.0, v39
	v_lshlrev_b32_e32 v39, 16, v44
	v_mul_f32_e32 v39, 0xbfb8aa3b, v39
	v_exp_f32_e32 v39, v39
	v_rcp_f32_e32 v54, v38
	v_add_f32_e32 v38, 1.0, v40
	v_and_b32_e32 v40, 0xffff0000, v44
	v_rcp_f32_e32 v44, v38
	v_add_f32_e32 v38, 1.0, v39
	v_rcp_f32_e32 v55, v38
	v_lshlrev_b32_e32 v38, 16, v45
	v_mul_f32_e32 v40, 0xbfb8aa3b, v40
	v_mul_f32_e32 v38, 0xbfb8aa3b, v38
	v_exp_f32_e32 v40, v40
	v_exp_f32_e32 v57, v38
	v_and_b32_e32 v38, 0xffff0000, v45
	v_mul_f32_e32 v38, 0xbfb8aa3b, v38
	v_exp_f32_e32 v45, v38
	v_add_f32_e32 v56, 1.0, v40
	global_load_dwordx4 v[38:41], v[52:53], off offset:256
	v_rcp_f32_e32 v52, v56
	v_add_f32_e32 v53, 1.0, v57
	v_rcp_f32_e32 v53, v53
	s_waitcnt vmcnt(3)
	v_lshlrev_b32_e32 v56, 16, v46
	v_add_f32_e32 v45, 1.0, v45
	v_fmac_f32_e32 v56, v30, v42
	v_and_b32_e32 v30, 0xffff0000, v46
	v_rcp_f32_e32 v45, v45
	v_fmac_f32_e32 v30, v31, v43
	v_lshlrev_b32_e32 v31, 16, v47
	v_fmac_f32_e32 v31, v32, v54
	v_and_b32_e32 v32, 0xffff0000, v47
	v_fmac_f32_e32 v32, v33, v44
	v_lshlrev_b32_e32 v33, 16, v48
	v_and_b32_e32 v42, 0xffff0000, v48
	v_lshlrev_b32_e32 v43, 16, v49
	v_fmac_f32_e32 v33, v26, v55
	v_fmac_f32_e32 v42, v27, v52
	v_fmac_f32_e32 v43, v28, v53
	v_and_b32_e32 v44, 0xffff0000, v49
	v_cvt_pk_bf16_f32 v26, v56, v30
	v_cvt_pk_bf16_f32 v27, v31, v32
	v_lshl_add_u64 v[30:31], s[2:3], 0, v[50:51]
	v_fmac_f32_e32 v44, v29, v45
	v_cvt_pk_bf16_f32 v28, v33, v42
	v_cvt_pk_bf16_f32 v29, v43, v44
	v_lshl_add_u64 v[42:43], v[30:31], 0, v[146:147]
	global_store_dwordx4 v[42:43], v[26:29], off
	v_add_u32_e32 v30, 0xb0, v148
	s_waitcnt vmcnt(2)
	v_and_b32_e32 v32, 0xffff0000, v34
	v_lshlrev_b32_e32 v26, 16, v34
	v_mul_f32_e32 v26, 0xbfb8aa3b, v26
	v_exp_f32_e32 v31, v26
	v_mad_i64_i32 v[26:27], s[24:25], v30, s45, v[150:151]
	v_lshl_add_u64 v[44:45], v[26:27], 0, v[146:147]
	global_load_dwordx4 v[26:29], v[44:45], off
	v_mul_f32_e32 v32, 0xbfb8aa3b, v32
	v_exp_f32_e32 v32, v32
	v_add_f32_e32 v31, 1.0, v31
	v_rcp_f32_e32 v46, v31
	v_and_b32_e32 v33, 0xffff0000, v35
	v_add_f32_e32 v31, 1.0, v32
	v_lshlrev_b32_e32 v32, 16, v35
	v_mul_f32_e32 v32, 0xbfb8aa3b, v32
	v_exp_f32_e32 v32, v32
	v_mul_f32_e32 v33, 0xbfb8aa3b, v33
	v_exp_f32_e32 v33, v33
	v_rcp_f32_e32 v47, v31
	v_add_f32_e32 v31, 1.0, v32
	v_lshlrev_b32_e32 v32, 16, v36
	v_rcp_f32_e32 v48, v31
	v_add_f32_e32 v31, 1.0, v33
	v_mul_f32_e32 v32, 0xbfb8aa3b, v32
	v_and_b32_e32 v33, 0xffff0000, v36
	v_exp_f32_e32 v32, v32
	v_mul_f32_e32 v33, 0xbfb8aa3b, v33
	v_exp_f32_e32 v33, v33
	v_rcp_f32_e32 v49, v31
	v_add_f32_e32 v31, 1.0, v32
	v_lshlrev_b32_e32 v32, 16, v37
	v_rcp_f32_e32 v50, v31
	v_add_f32_e32 v31, 1.0, v33
	v_mul_f32_e32 v32, 0xbfb8aa3b, v32
	v_and_b32_e32 v33, 0xffff0000, v37
	v_exp_f32_e32 v32, v32
	v_mul_f32_e32 v33, 0xbfb8aa3b, v33
	v_exp_f32_e32 v33, v33
	v_rcp_f32_e32 v51, v31
	v_add_f32_e32 v31, 1.0, v32
	v_rcp_f32_e32 v52, v31
	v_add_f32_e32 v31, 1.0, v33
	v_rcp_f32_e32 v53, v31
	v_ashrrev_i32_e32 v31, 31, v30
	v_lshlrev_b64 v[34:35], 12, v[30:31]
	v_lshl_add_u64 v[30:31], s[6:7], 0, v[34:35]
	v_lshl_add_u64 v[36:37], v[30:31], 0, v[146:147]
	global_load_dwordx4 v[30:33], v[36:37], off
	s_waitcnt vmcnt(3)
	v_lshlrev_b32_e32 v54, 16, v38
	v_fmac_f32_e32 v54, v22, v46
	v_and_b32_e32 v22, 0xffff0000, v38
	v_fmac_f32_e32 v22, v23, v47
	v_lshlrev_b32_e32 v23, 16, v39
	v_fmac_f32_e32 v23, v24, v48
	v_and_b32_e32 v24, 0xffff0000, v39
	v_fmac_f32_e32 v24, v25, v49
	v_lshlrev_b32_e32 v25, 16, v40
	v_and_b32_e32 v38, 0xffff0000, v40
	v_lshlrev_b32_e32 v39, 16, v41
	v_and_b32_e32 v40, 0xffff0000, v41
	v_fmac_f32_e32 v25, v18, v50
	v_fmac_f32_e32 v38, v19, v51
	v_fmac_f32_e32 v39, v20, v52
	v_fmac_f32_e32 v40, v21, v53
	v_cvt_pk_bf16_f32 v18, v54, v22
	v_cvt_pk_bf16_f32 v19, v23, v24
	v_cvt_pk_bf16_f32 v20, v25, v38
	v_cvt_pk_bf16_f32 v21, v39, v40
	global_store_dwordx4 v[42:43], v[18:21], off offset:256
	global_load_dwordx4 v[18:21], v[44:45], off offset:256
	s_waitcnt vmcnt(3)
	v_lshlrev_b32_e32 v22, 16, v26
	v_mul_f32_e32 v22, 0xbfb8aa3b, v22
	v_and_b32_e32 v23, 0xffff0000, v26
	v_exp_f32_e32 v22, v22
	v_mul_f32_e32 v23, 0xbfb8aa3b, v23
	v_exp_f32_e32 v23, v23
	v_and_b32_e32 v24, 0xffff0000, v27
	v_add_f32_e32 v22, 1.0, v22
	v_rcp_f32_e32 v26, v22
	v_add_f32_e32 v22, 1.0, v23
	v_lshlrev_b32_e32 v23, 16, v27
	v_mul_f32_e32 v23, 0xbfb8aa3b, v23
	v_exp_f32_e32 v23, v23
	v_mul_f32_e32 v24, 0xbfb8aa3b, v24
	v_exp_f32_e32 v24, v24
	v_rcp_f32_e32 v27, v22
	v_add_f32_e32 v22, 1.0, v23
	v_rcp_f32_e32 v38, v22
	v_lshlrev_b32_e32 v22, 16, v28
	v_mul_f32_e32 v22, 0xbfb8aa3b, v22
	v_exp_f32_e32 v40, v22
	v_and_b32_e32 v22, 0xffff0000, v28
	v_add_f32_e32 v39, 1.0, v24
	v_mul_f32_e32 v28, 0xbfb8aa3b, v22
	global_load_dwordx4 v[22:25], v[36:37], off offset:256
	v_rcp_f32_e32 v36, v39
	v_lshlrev_b32_e32 v39, 16, v29
	v_mul_f32_e32 v39, 0xbfb8aa3b, v39
	v_exp_f32_e32 v28, v28
	v_exp_f32_e32 v39, v39
	v_and_b32_e32 v29, 0xffff0000, v29
	v_add_f32_e32 v37, 1.0, v40
	v_mul_f32_e32 v29, 0xbfb8aa3b, v29
	v_rcp_f32_e32 v37, v37
	v_add_f32_e32 v28, 1.0, v28
	v_exp_f32_e32 v29, v29
	v_add_f32_e32 v39, 1.0, v39
	v_rcp_f32_e32 v28, v28
	v_rcp_f32_e32 v39, v39
	v_add_f32_e32 v29, 1.0, v29
	v_rcp_f32_e32 v29, v29
	s_waitcnt vmcnt(3)
	v_lshlrev_b32_e32 v40, 16, v30
	v_fmac_f32_e32 v40, v14, v26
	v_and_b32_e32 v14, 0xffff0000, v30
	v_fmac_f32_e32 v14, v15, v27
	v_lshlrev_b32_e32 v15, 16, v31
	v_fmac_f32_e32 v15, v16, v38
	v_and_b32_e32 v16, 0xffff0000, v31
	v_fmac_f32_e32 v16, v17, v36
	v_lshlrev_b32_e32 v17, 16, v32
	v_fmac_f32_e32 v17, v10, v37
	v_and_b32_e32 v26, 0xffff0000, v32
	v_lshlrev_b32_e32 v27, 16, v33
	v_fmac_f32_e32 v26, v11, v28
	v_fmac_f32_e32 v27, v12, v39
	v_cvt_pk_bf16_f32 v11, v15, v16
	v_cvt_pk_bf16_f32 v12, v17, v26
	v_cvt_pk_bf16_f32 v10, v40, v14
	v_lshl_add_u64 v[14:15], s[2:3], 0, v[34:35]
	v_and_b32_e32 v28, 0xffff0000, v33
	v_lshl_add_u64 v[14:15], v[14:15], 0, v[146:147]
	v_fmac_f32_e32 v28, v13, v29
	v_cvt_pk_bf16_f32 v13, v27, v28
	global_store_dwordx4 v[14:15], v[10:13], off
	s_waitcnt vmcnt(2)
	v_lshlrev_b32_e32 v16, 16, v18
	v_and_b32_e32 v17, 0xffff0000, v18
	v_mul_f32_e32 v16, 0xbfb8aa3b, v16
	v_mul_f32_e32 v17, 0xbfb8aa3b, v17
	v_exp_f32_e32 v16, v16
	v_exp_f32_e32 v17, v17
	v_lshlrev_b32_e32 v12, 16, v19
	v_mul_f32_e32 v12, 0xbfb8aa3b, v12
	v_and_b32_e32 v13, 0xffff0000, v19
	v_add_f32_e32 v10, 1.0, v16
	v_add_f32_e32 v11, 1.0, v17
	v_exp_f32_e32 v12, v12
	v_mul_f32_e32 v13, 0xbfb8aa3b, v13
	v_lshlrev_b32_e32 v16, 16, v20
	v_and_b32_e32 v17, 0xffff0000, v20
	v_lshlrev_b32_e32 v18, 16, v21
	v_and_b32_e32 v19, 0xffff0000, v21
	v_exp_f32_e32 v13, v13
	v_mul_f32_e32 v16, 0xbfb8aa3b, v16
	v_mul_f32_e32 v17, 0xbfb8aa3b, v17
	v_mul_f32_e32 v18, 0xbfb8aa3b, v18
	v_mul_f32_e32 v19, 0xbfb8aa3b, v19
	v_exp_f32_e32 v16, v16
	v_exp_f32_e32 v17, v17
	v_exp_f32_e32 v18, v18
	v_exp_f32_e32 v19, v19
	v_rcp_f32_e32 v10, v10
	v_rcp_f32_e32 v11, v11
	v_add_f32_e32 v12, 1.0, v12
	v_rcp_f32_e32 v12, v12
	v_add_f32_e32 v13, 1.0, v13
	v_rcp_f32_e32 v13, v13
	v_add_f32_e32 v16, 1.0, v16
	v_add_f32_e32 v17, 1.0, v17
	v_add_f32_e32 v18, 1.0, v18
	v_add_f32_e32 v19, 1.0, v19
	v_rcp_f32_e32 v16, v16
	v_rcp_f32_e32 v17, v17
	v_rcp_f32_e32 v18, v18
	v_rcp_f32_e32 v19, v19
	s_waitcnt vmcnt(1)
	v_lshlrev_b32_e32 v20, 16, v22
	v_fmac_f32_e32 v20, v6, v10
	v_and_b32_e32 v6, 0xffff0000, v22
	v_fmac_f32_e32 v6, v7, v11
	v_lshlrev_b32_e32 v7, 16, v23
	v_fmac_f32_e32 v7, v8, v12
	v_and_b32_e32 v8, 0xffff0000, v23
	v_fmac_f32_e32 v8, v9, v13
	v_lshlrev_b32_e32 v9, 16, v24
	v_and_b32_e32 v10, 0xffff0000, v24
	v_lshlrev_b32_e32 v11, 16, v25
	v_and_b32_e32 v12, 0xffff0000, v25
	v_fmac_f32_e32 v9, v2, v16
	v_fmac_f32_e32 v10, v3, v17
	v_fmac_f32_e32 v11, v4, v18
	v_fmac_f32_e32 v12, v5, v19
	v_cvt_pk_bf16_f32 v2, v20, v6
	v_cvt_pk_bf16_f32 v3, v7, v8
	v_cvt_pk_bf16_f32 v4, v9, v10
	v_cvt_pk_bf16_f32 v5, v11, v12
	global_store_dwordx4 v[14:15], v[2:5], off offset:256
	s_cbranch_vccnz .LBB0_907
	s_andn2_b64 vcc, exec, s[0:1]
	s_cbranch_vccnz .LBB0_906
	s_barrier
	s_branch .LBB0_906

	.amdhsa_kernel _Z10fwd_kernel6Params
		.amdhsa_group_segment_fixed_size 0
		.amdhsa_private_segment_fixed_size 0
		.amdhsa_kernarg_size 520
		.amdhsa_user_sgpr_count 2
		.amdhsa_user_sgpr_dispatch_ptr 0
		.amdhsa_user_sgpr_queue_ptr 0
		.amdhsa_user_sgpr_kernarg_segment_ptr 1
		.amdhsa_user_sgpr_dispatch_id 0
		.amdhsa_user_sgpr_kernarg_preload_length 0
		.amdhsa_user_sgpr_kernarg_preload_offset 0
		.amdhsa_user_sgpr_private_segment_size 0
		.amdhsa_uses_dynamic_stack 0
		.amdhsa_enable_private_segment 0
		.amdhsa_system_sgpr_workgroup_id_x 1
		.amdhsa_system_sgpr_workgroup_id_y 0
		.amdhsa_system_sgpr_workgroup_id_z 0
		.amdhsa_system_sgpr_workgroup_info 0
		.amdhsa_system_vgpr_workitem_id 2
		.amdhsa_next_free_vgpr 240
		.amdhsa_next_free_sgpr 102
		.amdhsa_accum_offset 240
		.amdhsa_reserve_vcc 1
		.amdhsa_float_round_mode_32 0
		.amdhsa_float_round_mode_16_64 0
		.amdhsa_float_denorm_mode_32 3
		.amdhsa_float_denorm_mode_16_64 3
		.amdhsa_dx10_clamp 1
		.amdhsa_ieee_mode 1
		.amdhsa_fp16_overflow 0
		.amdhsa_tg_split 0
		.amdhsa_exception_fp_ieee_invalid_op 0
		.amdhsa_exception_fp_denorm_src 0
		.amdhsa_exception_fp_ieee_div_zero 0
		.amdhsa_exception_fp_ieee_overflow 0
		.amdhsa_exception_fp_ieee_underflow 0
		.amdhsa_exception_fp_ieee_inexact 0
		.amdhsa_exception_int_div_zero 0
	.end_amdhsa_kernel

amdhsa.kernels:
  - .agpr_count:     0
    .args:
      - .offset:         0
        .size:           264
        .value_kind:     by_value
      - .offset:         264
        .size:           4
        .value_kind:     hidden_block_count_x
      - .offset:         268
        .size:           4
        .value_kind:     hidden_block_count_y
      - .offset:         272
        .size:           4
        .value_kind:     hidden_block_count_z
      - .offset:         276
        .size:           2
        .value_kind:     hidden_group_size_x
      - .offset:         278
        .size:           2
        .value_kind:     hidden_group_size_y
      - .offset:         280
        .size:           2
        .value_kind:     hidden_group_size_z
      - .offset:         282
        .size:           2
        .value_kind:     hidden_remainder_x
      - .offset:         284
        .size:           2
        .value_kind:     hidden_remainder_y
      - .offset:         286
        .size:           2
        .value_kind:     hidden_remainder_z
      - .offset:         304
        .size:           8
        .value_kind:     hidden_global_offset_x
      - .offset:         312
        .size:           8
        .value_kind:     hidden_global_offset_y
      - .offset:         320
        .size:           8
        .value_kind:     hidden_global_offset_z
      - .offset:         328
        .size:           2
        .value_kind:     hidden_grid_dims
      - .offset:         352
        .size:           8
        .value_kind:     hidden_multigrid_sync_arg
      - .offset:         384
        .size:           4
        .value_kind:     hidden_dynamic_lds_size
    .group_segment_fixed_size: 0
    .kernarg_segment_align: 8
    .kernarg_segment_size: 520
    .language:       OpenCL C
    .language_version:
      - 2
      - 0
    .max_flat_workgroup_size: 512
    .name:           _Z10fwd_kernel6Params
    .private_segment_fixed_size: 0
    .sgpr_count:     108
    .sgpr_spill_count: 105
    .symbol:         _Z10fwd_kernel6Params.kd
    .uniform_work_group_size: 1
    .uses_dynamic_stack: false
    .vgpr_count:     240
    .vgpr_spill_count: 0
    .wavefront_size: 64
